# ph12a, ph6a, ph6b epilogues: per-row residual/gate loads software-prefetched (2-4 rows in flight, saddr form, dead fragment regs); arithmetic unchanged
# baseline (speedup 1.0000x reference)
.LBB0_798:
	v_lshl_add_u32 v146, s38, 8, v157
	v_lshl_or_b32 v144, s61, 8, v159
	v_ashrrev_i32_e32 v147, 31, v146
	v_ashrrev_i32_e32 v145, 31, v144
	v_lshlrev_b64 v[164:165], 12, v[146:147]
	v_lshlrev_b64 v[144:145], 1, v[144:145]
	v_lshl_add_u64 v[164:165], s[70:71], 0, v[164:165]
	v_lshl_add_u64 v[168:169], v[164:165], 0, v[144:145]
	v_lshlrev_b32_e32 v224, 12, v146
	v_add_u32_e32 v224, v224, v144
	s_add_u32 s98, s70, 0x0
	s_addc_u32 s99, s71, 0
	global_load_dwordx4 v[176:179], v224, s[98:99]
	global_load_dwordx4 v[182:185], v224, s[98:99] offset:256
	s_add_u32 s98, s70, 0x10000
	s_addc_u32 s99, s71, 0
	global_load_dwordx4 v[186:189], v224, s[98:99]
	global_load_dwordx4 v[190:193], v224, s[98:99] offset:256
	s_add_u32 s98, s70, 0x20000
	s_addc_u32 s99, s71, 0
	global_load_dwordx4 v[194:197], v224, s[98:99]
	global_load_dwordx4 v[198:201], v224, s[98:99] offset:256
	s_add_u32 s98, s70, 0x30000
	s_addc_u32 s99, s71, 0
	global_load_dwordx4 v[202:205], v224, s[98:99]
	global_load_dwordx4 v[206:209], v224, s[98:99] offset:256
	v_lshlrev_b64 v[170:171], 11, v[146:147]
	v_lshl_add_u64 v[170:171], s[42:43], 0, v[170:171]
	v_lshl_add_u64 v[170:171], v[170:171], 0, v[144:145]
	s_andn2_b64 vcc, exec, s[0:1]
	s_mov_b64 s[0:1], -1
	s_waitcnt vmcnt(6)
	v_lshlrev_b32_e32 v172, 16, v176
	v_and_b32_e32 v173, 0xffff0000, v176
	v_lshlrev_b32_e32 v174, 16, v178
	v_and_b32_e32 v175, 0xffff0000, v178
	v_lshlrev_b32_e32 v164, 16, v177
	v_and_b32_e32 v165, 0xffff0000, v177
	v_lshlrev_b32_e32 v166, 16, v179
	v_and_b32_e32 v167, 0xffff0000, v179
	v_pk_mul_f32 v[124:125], v[124:125], v[172:173]
	v_pk_mul_f32 v[172:173], v[120:121], v[174:175]
	v_pk_mul_f32 v[126:127], v[126:127], v[164:165]
	v_pk_mul_f32 v[164:165], v[122:123], v[166:167]
	v_cvt_pk_bf16_f32 v120, v124, v125
	v_cvt_pk_bf16_f32 v121, v126, v127
	v_cvt_pk_bf16_f32 v122, v172, v173
	v_cvt_pk_bf16_f32 v123, v164, v165
	global_store_dwordx4 v[170:171], v[120:123], off
	v_or_b32_e32 v124, 16, v146
	v_ashrrev_i32_e32 v125, 31, v124
	v_lshlrev_b64 v[126:127], 12, v[124:125]
	v_lshl_add_u64 v[126:127], s[70:71], 0, v[126:127]
	v_lshl_add_u64 v[126:127], v[126:127], 0, v[144:145]
	v_lshlrev_b32_e32 v164, 16, v182
	v_and_b32_e32 v165, 0xffff0000, v182
	v_lshlrev_b32_e32 v166, 16, v184
	v_and_b32_e32 v167, 0xffff0000, v184
	v_lshlrev_b32_e32 v120, 16, v183
	v_and_b32_e32 v121, 0xffff0000, v183
	v_lshlrev_b32_e32 v122, 16, v185
	v_and_b32_e32 v123, 0xffff0000, v185
	v_pk_mul_f32 v[116:117], v[116:117], v[164:165]
	v_pk_mul_f32 v[164:165], v[112:113], v[166:167]
	v_pk_mul_f32 v[118:119], v[118:119], v[120:121]
	v_pk_mul_f32 v[120:121], v[114:115], v[122:123]
	v_cvt_pk_bf16_f32 v112, v116, v117
	v_cvt_pk_bf16_f32 v113, v118, v119
	v_cvt_pk_bf16_f32 v114, v164, v165
	v_cvt_pk_bf16_f32 v115, v120, v121
	global_store_dwordx4 v[170:171], v[112:115], off offset:256
	s_add_u32 s98, s70, 0x80000
	s_addc_u32 s99, s71, 0
	global_load_dwordx4 v[176:179], v224, s[98:99]
	global_load_dwordx4 v[182:185], v224, s[98:99] offset:256
	v_lshlrev_b64 v[116:117], 11, v[124:125]
	v_lshl_add_u64 v[116:117], s[42:43], 0, v[116:117]
	v_lshl_add_u64 v[116:117], v[116:117], 0, v[144:145]
	s_waitcnt vmcnt(8)
	v_lshlrev_b32_e32 v118, 16, v186
	v_and_b32_e32 v119, 0xffff0000, v186
	v_lshlrev_b32_e32 v120, 16, v188
	v_and_b32_e32 v121, 0xffff0000, v188
	v_lshlrev_b32_e32 v112, 16, v187
	v_and_b32_e32 v113, 0xffff0000, v187
	v_lshlrev_b32_e32 v114, 16, v189
	v_and_b32_e32 v115, 0xffff0000, v189
	v_pk_mul_f32 v[108:109], v[108:109], v[118:119]
	v_pk_mul_f32 v[118:119], v[104:105], v[120:121]
	v_pk_mul_f32 v[110:111], v[110:111], v[112:113]
	v_pk_mul_f32 v[112:113], v[106:107], v[114:115]
	v_cvt_pk_bf16_f32 v104, v108, v109
	v_cvt_pk_bf16_f32 v105, v110, v111
	v_cvt_pk_bf16_f32 v106, v118, v119
	v_cvt_pk_bf16_f32 v107, v112, v113
	global_store_dwordx4 v[116:117], v[104:107], off
	v_or_b32_e32 v108, 32, v146
	v_ashrrev_i32_e32 v109, 31, v108
	v_lshlrev_b64 v[110:111], 12, v[108:109]
	v_lshl_add_u64 v[110:111], s[70:71], 0, v[110:111]
	v_lshl_add_u64 v[110:111], v[110:111], 0, v[144:145]
	v_lshlrev_b32_e32 v112, 16, v190
	v_and_b32_e32 v113, 0xffff0000, v190
	v_lshlrev_b32_e32 v114, 16, v192
	v_and_b32_e32 v115, 0xffff0000, v192
	v_lshlrev_b32_e32 v104, 16, v191
	v_and_b32_e32 v105, 0xffff0000, v191
	v_lshlrev_b32_e32 v106, 16, v193
	v_and_b32_e32 v107, 0xffff0000, v193
	v_pk_mul_f32 v[100:101], v[100:101], v[112:113]
	v_pk_mul_f32 v[112:113], v[96:97], v[114:115]
	v_pk_mul_f32 v[102:103], v[102:103], v[104:105]
	v_pk_mul_f32 v[104:105], v[98:99], v[106:107]
	v_cvt_pk_bf16_f32 v96, v100, v101
	v_cvt_pk_bf16_f32 v97, v102, v103
	v_cvt_pk_bf16_f32 v98, v112, v113
	v_cvt_pk_bf16_f32 v99, v104, v105
	global_store_dwordx4 v[116:117], v[96:99], off offset:256
	s_add_u32 s98, s70, 0x90000
	s_addc_u32 s99, s71, 0
	global_load_dwordx4 v[186:189], v224, s[98:99]
	global_load_dwordx4 v[190:193], v224, s[98:99] offset:256
	v_lshlrev_b64 v[100:101], 11, v[108:109]
	v_lshl_add_u64 v[100:101], s[42:43], 0, v[100:101]
	v_lshl_add_u64 v[100:101], v[100:101], 0, v[144:145]
	s_waitcnt vmcnt(10)
	v_lshlrev_b32_e32 v102, 16, v194
	v_and_b32_e32 v103, 0xffff0000, v194
	v_lshlrev_b32_e32 v104, 16, v196
	v_and_b32_e32 v105, 0xffff0000, v196
	v_lshlrev_b32_e32 v96, 16, v195
	v_and_b32_e32 v97, 0xffff0000, v195
	v_lshlrev_b32_e32 v98, 16, v197
	v_and_b32_e32 v99, 0xffff0000, v197
	v_pk_mul_f32 v[92:93], v[92:93], v[102:103]
	v_pk_mul_f32 v[102:103], v[88:89], v[104:105]
	v_pk_mul_f32 v[94:95], v[94:95], v[96:97]
	v_pk_mul_f32 v[96:97], v[90:91], v[98:99]
	v_cvt_pk_bf16_f32 v88, v92, v93
	v_cvt_pk_bf16_f32 v89, v94, v95
	v_cvt_pk_bf16_f32 v90, v102, v103
	v_cvt_pk_bf16_f32 v91, v96, v97
	global_store_dwordx4 v[100:101], v[88:91], off
	v_or_b32_e32 v92, 48, v146
	v_ashrrev_i32_e32 v93, 31, v92
	v_lshlrev_b64 v[94:95], 12, v[92:93]
	v_lshl_add_u64 v[94:95], s[70:71], 0, v[94:95]
	v_lshl_add_u64 v[94:95], v[94:95], 0, v[144:145]
	v_lshlrev_b32_e32 v96, 16, v198
	v_and_b32_e32 v97, 0xffff0000, v198
	v_lshlrev_b32_e32 v98, 16, v200
	v_and_b32_e32 v99, 0xffff0000, v200
	v_lshlrev_b32_e32 v88, 16, v199
	v_and_b32_e32 v89, 0xffff0000, v199
	v_lshlrev_b32_e32 v90, 16, v201
	v_and_b32_e32 v91, 0xffff0000, v201
	v_pk_mul_f32 v[84:85], v[84:85], v[96:97]
	v_pk_mul_f32 v[96:97], v[80:81], v[98:99]
	v_pk_mul_f32 v[86:87], v[86:87], v[88:89]
	v_pk_mul_f32 v[88:89], v[82:83], v[90:91]
	v_cvt_pk_bf16_f32 v80, v84, v85
	v_cvt_pk_bf16_f32 v81, v86, v87
	v_cvt_pk_bf16_f32 v82, v96, v97
	v_cvt_pk_bf16_f32 v83, v88, v89
	global_store_dwordx4 v[100:101], v[80:83], off offset:256
	s_add_u32 s98, s70, 0xa0000
	s_addc_u32 s99, s71, 0
	global_load_dwordx4 v[194:197], v224, s[98:99]
	global_load_dwordx4 v[198:201], v224, s[98:99] offset:256
	v_lshlrev_b64 v[84:85], 11, v[92:93]
	v_lshl_add_u64 v[84:85], s[42:43], 0, v[84:85]
	v_lshl_add_u64 v[84:85], v[84:85], 0, v[144:145]
	s_waitcnt vmcnt(12)
	v_lshlrev_b32_e32 v86, 16, v202
	v_and_b32_e32 v87, 0xffff0000, v202
	v_lshlrev_b32_e32 v88, 16, v204
	v_and_b32_e32 v89, 0xffff0000, v204
	v_lshlrev_b32_e32 v80, 16, v203
	v_and_b32_e32 v81, 0xffff0000, v203
	v_lshlrev_b32_e32 v82, 16, v205
	v_and_b32_e32 v83, 0xffff0000, v205
	v_pk_mul_f32 v[76:77], v[76:77], v[86:87]
	v_pk_mul_f32 v[86:87], v[72:73], v[88:89]
	v_pk_mul_f32 v[78:79], v[78:79], v[80:81]
	v_pk_mul_f32 v[80:81], v[74:75], v[82:83]
	v_cvt_pk_bf16_f32 v72, v76, v77
	v_cvt_pk_bf16_f32 v73, v78, v79
	v_cvt_pk_bf16_f32 v74, v86, v87
	v_cvt_pk_bf16_f32 v75, v80, v81
	global_store_dwordx4 v[84:85], v[72:75], off
	v_add_u32_e32 v76, 0x80, v146
	v_ashrrev_i32_e32 v77, 31, v76
	v_lshlrev_b64 v[78:79], 12, v[76:77]
	v_lshl_add_u64 v[78:79], s[70:71], 0, v[78:79]
	v_lshl_add_u64 v[78:79], v[78:79], 0, v[144:145]
	v_lshlrev_b32_e32 v80, 16, v206
	v_and_b32_e32 v81, 0xffff0000, v206
	v_lshlrev_b32_e32 v82, 16, v208
	v_and_b32_e32 v83, 0xffff0000, v208
	v_lshlrev_b32_e32 v72, 16, v207
	v_and_b32_e32 v73, 0xffff0000, v207
	v_lshlrev_b32_e32 v74, 16, v209
	v_and_b32_e32 v75, 0xffff0000, v209
	v_pk_mul_f32 v[68:69], v[68:69], v[80:81]
	v_pk_mul_f32 v[80:81], v[64:65], v[82:83]
	v_pk_mul_f32 v[70:71], v[70:71], v[72:73]
	v_pk_mul_f32 v[72:73], v[66:67], v[74:75]
	v_cvt_pk_bf16_f32 v64, v68, v69
	v_cvt_pk_bf16_f32 v65, v70, v71
	v_cvt_pk_bf16_f32 v66, v80, v81
	v_cvt_pk_bf16_f32 v67, v72, v73
	global_store_dwordx4 v[84:85], v[64:67], off offset:256
	s_add_u32 s98, s70, 0xb0000
	s_addc_u32 s99, s71, 0
	global_load_dwordx4 v[202:205], v224, s[98:99]
	global_load_dwordx4 v[206:209], v224, s[98:99] offset:256
	v_lshlrev_b64 v[68:69], 11, v[76:77]
	v_lshl_add_u64 v[68:69], s[42:43], 0, v[68:69]
	v_lshl_add_u64 v[68:69], v[68:69], 0, v[144:145]
	s_waitcnt vmcnt(12)
	v_lshlrev_b32_e32 v70, 16, v176
	v_and_b32_e32 v71, 0xffff0000, v176
	v_lshlrev_b32_e32 v72, 16, v178
	v_and_b32_e32 v73, 0xffff0000, v178
	v_lshlrev_b32_e32 v64, 16, v177
	v_and_b32_e32 v65, 0xffff0000, v177
	v_lshlrev_b32_e32 v66, 16, v179
	v_and_b32_e32 v67, 0xffff0000, v179
	v_pk_mul_f32 v[60:61], v[60:61], v[70:71]
	v_pk_mul_f32 v[70:71], v[56:57], v[72:73]
	v_pk_mul_f32 v[62:63], v[62:63], v[64:65]
	v_pk_mul_f32 v[64:65], v[58:59], v[66:67]
	v_cvt_pk_bf16_f32 v56, v60, v61
	v_cvt_pk_bf16_f32 v57, v62, v63
	v_cvt_pk_bf16_f32 v58, v70, v71
	v_cvt_pk_bf16_f32 v59, v64, v65
	global_store_dwordx4 v[68:69], v[56:59], off
	v_add_u32_e32 v60, 0x90, v146
	v_ashrrev_i32_e32 v61, 31, v60
	v_lshlrev_b64 v[62:63], 12, v[60:61]
	v_lshl_add_u64 v[62:63], s[70:71], 0, v[62:63]
	v_lshl_add_u64 v[62:63], v[62:63], 0, v[144:145]
	v_lshlrev_b32_e32 v64, 16, v182
	v_and_b32_e32 v65, 0xffff0000, v182
	v_lshlrev_b32_e32 v66, 16, v184
	v_and_b32_e32 v67, 0xffff0000, v184
	v_lshlrev_b32_e32 v56, 16, v183
	v_and_b32_e32 v57, 0xffff0000, v183
	v_lshlrev_b32_e32 v58, 16, v185
	v_and_b32_e32 v59, 0xffff0000, v185
	v_pk_mul_f32 v[52:53], v[52:53], v[64:65]
	v_pk_mul_f32 v[64:65], v[48:49], v[66:67]
	v_pk_mul_f32 v[54:55], v[54:55], v[56:57]
	v_pk_mul_f32 v[56:57], v[50:51], v[58:59]
	v_cvt_pk_bf16_f32 v48, v52, v53
	v_cvt_pk_bf16_f32 v49, v54, v55
	v_cvt_pk_bf16_f32 v50, v64, v65
	v_cvt_pk_bf16_f32 v51, v56, v57
	global_store_dwordx4 v[68:69], v[48:51], off offset:256
	v_lshlrev_b64 v[52:53], 11, v[60:61]
	v_lshl_add_u64 v[52:53], s[42:43], 0, v[52:53]
	v_lshl_add_u64 v[52:53], v[52:53], 0, v[144:145]
	s_waitcnt vmcnt(10)
	v_lshlrev_b32_e32 v54, 16, v186
	v_and_b32_e32 v55, 0xffff0000, v186
	v_lshlrev_b32_e32 v56, 16, v188
	v_and_b32_e32 v57, 0xffff0000, v188
	v_lshlrev_b32_e32 v48, 16, v187
	v_and_b32_e32 v49, 0xffff0000, v187
	v_lshlrev_b32_e32 v50, 16, v189
	v_and_b32_e32 v51, 0xffff0000, v189
	v_pk_mul_f32 v[44:45], v[44:45], v[54:55]
	v_pk_mul_f32 v[54:55], v[40:41], v[56:57]
	v_pk_mul_f32 v[46:47], v[46:47], v[48:49]
	v_pk_mul_f32 v[48:49], v[42:43], v[50:51]
	v_cvt_pk_bf16_f32 v40, v44, v45
	v_cvt_pk_bf16_f32 v41, v46, v47
	v_cvt_pk_bf16_f32 v42, v54, v55
	v_cvt_pk_bf16_f32 v43, v48, v49
	global_store_dwordx4 v[52:53], v[40:43], off
	v_add_u32_e32 v44, 0xa0, v146
	v_ashrrev_i32_e32 v45, 31, v44
	v_lshlrev_b64 v[46:47], 12, v[44:45]
	v_lshl_add_u64 v[46:47], s[70:71], 0, v[46:47]
	v_lshl_add_u64 v[46:47], v[46:47], 0, v[144:145]
	v_lshlrev_b32_e32 v48, 16, v190
	v_and_b32_e32 v49, 0xffff0000, v190
	v_lshlrev_b32_e32 v50, 16, v192
	v_and_b32_e32 v51, 0xffff0000, v192
	v_lshlrev_b32_e32 v40, 16, v191
	v_and_b32_e32 v41, 0xffff0000, v191
	v_lshlrev_b32_e32 v42, 16, v193
	v_and_b32_e32 v43, 0xffff0000, v193
	v_pk_mul_f32 v[36:37], v[36:37], v[48:49]
	v_pk_mul_f32 v[48:49], v[32:33], v[50:51]
	v_pk_mul_f32 v[38:39], v[38:39], v[40:41]
	v_pk_mul_f32 v[40:41], v[34:35], v[42:43]
	v_cvt_pk_bf16_f32 v32, v36, v37
	v_cvt_pk_bf16_f32 v33, v38, v39
	v_cvt_pk_bf16_f32 v34, v48, v49
	v_cvt_pk_bf16_f32 v35, v40, v41
	global_store_dwordx4 v[52:53], v[32:35], off offset:256
	v_lshlrev_b64 v[36:37], 11, v[44:45]
	v_lshl_add_u64 v[36:37], s[42:43], 0, v[36:37]
	v_lshl_add_u64 v[36:37], v[36:37], 0, v[144:145]
	s_waitcnt vmcnt(8)
	v_lshlrev_b32_e32 v38, 16, v194
	v_and_b32_e32 v39, 0xffff0000, v194
	v_lshlrev_b32_e32 v40, 16, v196
	v_and_b32_e32 v41, 0xffff0000, v196
	v_lshlrev_b32_e32 v32, 16, v195
	v_and_b32_e32 v33, 0xffff0000, v195
	v_lshlrev_b32_e32 v34, 16, v197
	v_and_b32_e32 v35, 0xffff0000, v197
	v_pk_mul_f32 v[28:29], v[28:29], v[38:39]
	v_pk_mul_f32 v[38:39], v[24:25], v[40:41]
	v_pk_mul_f32 v[30:31], v[30:31], v[32:33]
	v_pk_mul_f32 v[32:33], v[26:27], v[34:35]
	v_cvt_pk_bf16_f32 v24, v28, v29
	v_cvt_pk_bf16_f32 v25, v30, v31
	v_cvt_pk_bf16_f32 v26, v38, v39
	v_cvt_pk_bf16_f32 v27, v32, v33
	global_store_dwordx4 v[36:37], v[24:27], off
	v_add_u32_e32 v28, 0xb0, v146
	v_ashrrev_i32_e32 v29, 31, v28
	v_lshlrev_b64 v[30:31], 12, v[28:29]
	v_lshl_add_u64 v[30:31], s[70:71], 0, v[30:31]
	v_lshl_add_u64 v[30:31], v[30:31], 0, v[144:145]
	v_lshlrev_b32_e32 v32, 16, v198
	v_and_b32_e32 v33, 0xffff0000, v198
	v_lshlrev_b32_e32 v34, 16, v200
	v_and_b32_e32 v35, 0xffff0000, v200
	v_lshlrev_b32_e32 v24, 16, v199
	v_and_b32_e32 v25, 0xffff0000, v199
	v_lshlrev_b32_e32 v26, 16, v201
	v_and_b32_e32 v27, 0xffff0000, v201
	v_pk_mul_f32 v[20:21], v[20:21], v[32:33]
	v_pk_mul_f32 v[32:33], v[16:17], v[34:35]
	v_pk_mul_f32 v[22:23], v[22:23], v[24:25]
	v_pk_mul_f32 v[24:25], v[18:19], v[26:27]
	v_cvt_pk_bf16_f32 v16, v20, v21
	v_cvt_pk_bf16_f32 v17, v22, v23
	v_cvt_pk_bf16_f32 v18, v32, v33
	v_cvt_pk_bf16_f32 v19, v24, v25
	global_store_dwordx4 v[36:37], v[16:19], off offset:256
	v_lshlrev_b64 v[20:21], 11, v[28:29]
	v_lshl_add_u64 v[20:21], s[42:43], 0, v[20:21]
	v_lshl_add_u64 v[20:21], v[20:21], 0, v[144:145]
	s_waitcnt vmcnt(6)
	v_lshlrev_b32_e32 v22, 16, v202
	v_and_b32_e32 v23, 0xffff0000, v202
	v_lshlrev_b32_e32 v24, 16, v204
	v_and_b32_e32 v25, 0xffff0000, v204
	v_lshlrev_b32_e32 v16, 16, v203
	v_and_b32_e32 v17, 0xffff0000, v203
	v_lshlrev_b32_e32 v18, 16, v205
	v_and_b32_e32 v19, 0xffff0000, v205
	v_pk_mul_f32 v[12:13], v[12:13], v[22:23]
	v_pk_mul_f32 v[22:23], v[8:9], v[24:25]
	v_pk_mul_f32 v[14:15], v[14:15], v[16:17]
	v_pk_mul_f32 v[16:17], v[10:11], v[18:19]
	v_cvt_pk_bf16_f32 v8, v12, v13
	v_cvt_pk_bf16_f32 v9, v14, v15
	v_cvt_pk_bf16_f32 v10, v22, v23
	v_cvt_pk_bf16_f32 v11, v16, v17
	global_store_dwordx4 v[20:21], v[8:11], off
	v_lshlrev_b32_e32 v12, 16, v206
	v_and_b32_e32 v13, 0xffff0000, v206
	v_lshlrev_b32_e32 v14, 16, v208
	v_and_b32_e32 v15, 0xffff0000, v208
	v_lshlrev_b32_e32 v8, 16, v207
	v_and_b32_e32 v9, 0xffff0000, v207
	v_lshlrev_b32_e32 v10, 16, v209
	v_and_b32_e32 v11, 0xffff0000, v209
	v_pk_mul_f32 v[4:5], v[4:5], v[12:13]
	v_pk_mul_f32 v[12:13], v[0:1], v[14:15]
	v_pk_mul_f32 v[6:7], v[6:7], v[8:9]
	v_pk_mul_f32 v[8:9], v[2:3], v[10:11]
	v_cvt_pk_bf16_f32 v0, v4, v5
	v_cvt_pk_bf16_f32 v1, v6, v7
	v_cvt_pk_bf16_f32 v2, v12, v13
	v_cvt_pk_bf16_f32 v3, v8, v9
	global_store_dwordx4 v[20:21], v[0:3], off offset:256
	s_cbranch_vccnz .LBB0_787
	s_andn2_b64 vcc, exec, s[16:17]
	s_cbranch_vccnz .LBB0_786
	s_barrier
	s_branch .LBB0_786

.LBB0_818:
	v_lshl_add_u32 v142, s28, 8, v144
	v_ashrrev_i32_e32 v143, 31, v142
	v_lshl_or_b32 v140, s66, 8, v146
	v_lshlrev_b64 v[150:151], 11, v[142:143]
	v_ashrrev_i32_e32 v141, 31, v140
	v_lshl_add_u64 v[154:155], s[42:43], 0, v[150:151]
	v_lshlrev_b64 v[150:151], 12, v[142:143]
	v_lshlrev_b64 v[140:141], 1, v[140:141]
	v_lshl_add_u64 v[150:151], s[70:71], 0, v[150:151]
	v_lshl_add_u64 v[164:165], v[150:151], 0, v[140:141]
	v_lshlrev_b32_e32 v212, 12, v142
	v_add_u32_e32 v212, v212, v140
	v_lshlrev_b32_e32 v213, 11, v142
	v_add_u32_e32 v213, v213, v140
	s_add_u32 s98, s70, 0x0
	s_addc_u32 s99, s71, 0
	s_add_u32 s100, s42, 0x0
	s_addc_u32 s101, s43, 0
	global_load_dwordx4 v[176:179], v212, s[98:99] offset:2048
	global_load_dwordx4 v[182:185], v213, s[100:101]
	global_load_dwordx4 v[186:189], v213, s[100:101] offset:256
	global_load_dwordx4 v[190:193], v212, s[98:99] offset:2304
	s_add_u32 s98, s70, 0x10000
	s_addc_u32 s99, s71, 0
	s_add_u32 s100, s42, 0x8000
	s_addc_u32 s101, s43, 0
	global_load_dwordx4 v[194:197], v212, s[98:99] offset:2048
	global_load_dwordx4 v[198:201], v213, s[100:101]
	global_load_dwordx4 v[202:205], v213, s[100:101] offset:256
	global_load_dwordx4 v[206:209], v212, s[98:99] offset:2304
	v_lshl_add_u64 v[166:167], v[154:155], 0, v[140:141]
	s_andn2_b64 vcc, exec, s[0:1]
	s_mov_b64 s[0:1], -1
	s_waitcnt vmcnt(4)
	v_lshlrev_b32_e32 v168, 16, v176
	v_and_b32_e32 v169, 0xffff0000, v176
	v_lshlrev_b32_e32 v170, 16, v182
	v_and_b32_e32 v171, 0xffff0000, v182
	v_lshlrev_b32_e32 v172, 16, v178
	v_and_b32_e32 v173, 0xffff0000, v178
	v_lshlrev_b32_e32 v174, 16, v184
	v_and_b32_e32 v175, 0xffff0000, v184
	v_lshlrev_b32_e32 v150, 16, v177
	v_and_b32_e32 v151, 0xffff0000, v177
	v_lshlrev_b32_e32 v154, 16, v183
	v_and_b32_e32 v155, 0xffff0000, v183
	v_lshlrev_b32_e32 v152, 16, v179
	v_and_b32_e32 v153, 0xffff0000, v179
	v_lshlrev_b32_e32 v156, 16, v185
	v_and_b32_e32 v157, 0xffff0000, v185
	v_pk_fma_f32 v[124:125], v[124:125], v[168:169], v[170:171]
	v_pk_fma_f32 v[168:169], v[120:121], v[172:173], v[174:175]
	v_pk_fma_f32 v[126:127], v[126:127], v[150:151], v[154:155]
	v_pk_fma_f32 v[150:151], v[122:123], v[152:153], v[156:157]
	v_cvt_pk_bf16_f32 v120, v124, v125
	v_cvt_pk_bf16_f32 v121, v126, v127
	v_cvt_pk_bf16_f32 v122, v168, v169
	v_cvt_pk_bf16_f32 v123, v150, v151
	global_store_dwordx4 v[166:167], v[120:123], off
	v_or_b32_e32 v124, 16, v142
	v_lshlrev_b32_e32 v150, 16, v186
	v_and_b32_e32 v151, 0xffff0000, v186
	v_lshlrev_b32_e32 v152, 16, v188
	v_and_b32_e32 v153, 0xffff0000, v188
	v_lshlrev_b32_e32 v154, 16, v187
	v_and_b32_e32 v155, 0xffff0000, v187
	v_lshlrev_b32_e32 v156, 16, v189
	v_and_b32_e32 v157, 0xffff0000, v189
	v_ashrrev_i32_e32 v125, 31, v124
	v_lshlrev_b64 v[126:127], 11, v[124:125]
	v_lshlrev_b64 v[124:125], 12, v[124:125]
	v_lshl_add_u64 v[124:125], s[70:71], 0, v[124:125]
	v_lshl_add_u64 v[126:127], s[42:43], 0, v[126:127]
	v_lshl_add_u64 v[124:125], v[124:125], 0, v[140:141]
	v_lshl_add_u64 v[126:127], v[126:127], 0, v[140:141]
	v_lshlrev_b32_e32 v158, 16, v190
	v_and_b32_e32 v159, 0xffff0000, v190
	v_lshlrev_b32_e32 v160, 16, v192
	v_and_b32_e32 v161, 0xffff0000, v192
	v_lshlrev_b32_e32 v120, 16, v191
	v_and_b32_e32 v121, 0xffff0000, v191
	v_lshlrev_b32_e32 v122, 16, v193
	v_and_b32_e32 v123, 0xffff0000, v193
	v_pk_fma_f32 v[116:117], v[116:117], v[158:159], v[150:151]
	v_pk_fma_f32 v[150:151], v[112:113], v[160:161], v[152:153]
	v_pk_fma_f32 v[118:119], v[118:119], v[120:121], v[154:155]
	v_pk_fma_f32 v[120:121], v[114:115], v[122:123], v[156:157]
	v_cvt_pk_bf16_f32 v112, v116, v117
	v_cvt_pk_bf16_f32 v113, v118, v119
	v_cvt_pk_bf16_f32 v114, v150, v151
	v_cvt_pk_bf16_f32 v115, v120, v121
	global_store_dwordx4 v[166:167], v[112:115], off offset:256
	s_add_u32 s98, s70, 0x20000
	s_addc_u32 s99, s71, 0
	s_add_u32 s100, s42, 0x10000
	s_addc_u32 s101, s43, 0
	global_load_dwordx4 v[176:179], v212, s[98:99] offset:2048
	global_load_dwordx4 v[182:185], v213, s[100:101]
	global_load_dwordx4 v[186:189], v213, s[100:101] offset:256
	global_load_dwordx4 v[190:193], v212, s[98:99] offset:2304
	s_waitcnt vmcnt(6)
	v_lshlrev_b32_e32 v152, 16, v198
	v_lshlrev_b32_e32 v150, 16, v194
	v_and_b32_e32 v151, 0xffff0000, v194
	v_and_b32_e32 v153, 0xffff0000, v198
	v_lshlrev_b32_e32 v154, 16, v196
	v_and_b32_e32 v155, 0xffff0000, v196
	v_lshlrev_b32_e32 v156, 16, v200
	v_and_b32_e32 v157, 0xffff0000, v200
	v_lshlrev_b32_e32 v112, 16, v195
	v_and_b32_e32 v113, 0xffff0000, v195
	v_lshlrev_b32_e32 v116, 16, v199
	v_and_b32_e32 v117, 0xffff0000, v199
	v_lshlrev_b32_e32 v114, 16, v197
	v_and_b32_e32 v115, 0xffff0000, v197
	v_lshlrev_b32_e32 v118, 16, v201
	v_and_b32_e32 v119, 0xffff0000, v201
	v_pk_fma_f32 v[108:109], v[108:109], v[150:151], v[152:153]
	v_pk_fma_f32 v[150:151], v[104:105], v[154:155], v[156:157]
	v_pk_fma_f32 v[110:111], v[110:111], v[112:113], v[116:117]
	v_pk_fma_f32 v[112:113], v[106:107], v[114:115], v[118:119]
	v_cvt_pk_bf16_f32 v104, v108, v109
	v_cvt_pk_bf16_f32 v105, v110, v111
	v_cvt_pk_bf16_f32 v106, v150, v151
	v_cvt_pk_bf16_f32 v107, v112, v113
	global_store_dwordx4 v[126:127], v[104:107], off
	v_or_b32_e32 v108, 32, v142
	v_lshlrev_b32_e32 v112, 16, v202
	v_and_b32_e32 v113, 0xffff0000, v202
	v_lshlrev_b32_e32 v114, 16, v204
	v_and_b32_e32 v115, 0xffff0000, v204
	v_lshlrev_b32_e32 v116, 16, v203
	v_and_b32_e32 v117, 0xffff0000, v203
	v_lshlrev_b32_e32 v118, 16, v205
	v_and_b32_e32 v119, 0xffff0000, v205
	v_ashrrev_i32_e32 v109, 31, v108
	v_lshlrev_b64 v[110:111], 11, v[108:109]
	v_lshlrev_b64 v[108:109], 12, v[108:109]
	v_lshl_add_u64 v[108:109], s[70:71], 0, v[108:109]
	v_lshl_add_u64 v[110:111], s[42:43], 0, v[110:111]
	v_lshl_add_u64 v[108:109], v[108:109], 0, v[140:141]
	v_lshl_add_u64 v[110:111], v[110:111], 0, v[140:141]
	v_lshlrev_b32_e32 v120, 16, v206
	v_and_b32_e32 v121, 0xffff0000, v206
	v_lshlrev_b32_e32 v122, 16, v208
	v_and_b32_e32 v123, 0xffff0000, v208
	v_lshlrev_b32_e32 v104, 16, v207
	v_and_b32_e32 v105, 0xffff0000, v207
	v_lshlrev_b32_e32 v106, 16, v209
	v_and_b32_e32 v107, 0xffff0000, v209
	v_pk_fma_f32 v[100:101], v[100:101], v[120:121], v[112:113]
	v_pk_fma_f32 v[112:113], v[96:97], v[122:123], v[114:115]
	v_pk_fma_f32 v[102:103], v[102:103], v[104:105], v[116:117]
	v_pk_fma_f32 v[104:105], v[98:99], v[106:107], v[118:119]
	v_cvt_pk_bf16_f32 v96, v100, v101
	v_cvt_pk_bf16_f32 v97, v102, v103
	v_cvt_pk_bf16_f32 v98, v112, v113
	v_cvt_pk_bf16_f32 v99, v104, v105
	global_store_dwordx4 v[126:127], v[96:99], off offset:256
	s_add_u32 s98, s70, 0x30000
	s_addc_u32 s99, s71, 0
	s_add_u32 s100, s42, 0x18000
	s_addc_u32 s101, s43, 0
	global_load_dwordx4 v[194:197], v212, s[98:99] offset:2048
	global_load_dwordx4 v[198:201], v213, s[100:101]
	global_load_dwordx4 v[202:205], v213, s[100:101] offset:256
	global_load_dwordx4 v[206:209], v212, s[98:99] offset:2304
	s_waitcnt vmcnt(6)
	v_lshlrev_b32_e32 v114, 16, v182
	v_lshlrev_b32_e32 v112, 16, v176
	v_and_b32_e32 v113, 0xffff0000, v176
	v_and_b32_e32 v115, 0xffff0000, v182
	v_lshlrev_b32_e32 v116, 16, v178
	v_and_b32_e32 v117, 0xffff0000, v178
	v_lshlrev_b32_e32 v118, 16, v184
	v_and_b32_e32 v119, 0xffff0000, v184
	v_lshlrev_b32_e32 v96, 16, v177
	v_and_b32_e32 v97, 0xffff0000, v177
	v_lshlrev_b32_e32 v100, 16, v183
	v_and_b32_e32 v101, 0xffff0000, v183
	v_lshlrev_b32_e32 v98, 16, v179
	v_and_b32_e32 v99, 0xffff0000, v179
	v_lshlrev_b32_e32 v102, 16, v185
	v_and_b32_e32 v103, 0xffff0000, v185
	v_pk_fma_f32 v[92:93], v[92:93], v[112:113], v[114:115]
	v_pk_fma_f32 v[112:113], v[88:89], v[116:117], v[118:119]
	v_pk_fma_f32 v[94:95], v[94:95], v[96:97], v[100:101]
	v_pk_fma_f32 v[96:97], v[90:91], v[98:99], v[102:103]
	v_cvt_pk_bf16_f32 v88, v92, v93
	v_cvt_pk_bf16_f32 v89, v94, v95
	v_cvt_pk_bf16_f32 v90, v112, v113
	v_cvt_pk_bf16_f32 v91, v96, v97
	global_store_dwordx4 v[110:111], v[88:91], off
	v_or_b32_e32 v92, 48, v142
	v_lshlrev_b32_e32 v96, 16, v186
	v_and_b32_e32 v97, 0xffff0000, v186
	v_lshlrev_b32_e32 v98, 16, v188
	v_and_b32_e32 v99, 0xffff0000, v188
	v_lshlrev_b32_e32 v100, 16, v187
	v_and_b32_e32 v101, 0xffff0000, v187
	v_lshlrev_b32_e32 v102, 16, v189
	v_and_b32_e32 v103, 0xffff0000, v189
	v_ashrrev_i32_e32 v93, 31, v92
	v_lshlrev_b64 v[94:95], 11, v[92:93]
	v_lshlrev_b64 v[92:93], 12, v[92:93]
	v_lshl_add_u64 v[92:93], s[70:71], 0, v[92:93]
	v_lshl_add_u64 v[94:95], s[42:43], 0, v[94:95]
	v_lshl_add_u64 v[92:93], v[92:93], 0, v[140:141]
	v_lshl_add_u64 v[94:95], v[94:95], 0, v[140:141]
	v_lshlrev_b32_e32 v104, 16, v190
	v_and_b32_e32 v105, 0xffff0000, v190
	v_lshlrev_b32_e32 v106, 16, v192
	v_and_b32_e32 v107, 0xffff0000, v192
	v_lshlrev_b32_e32 v88, 16, v191
	v_and_b32_e32 v89, 0xffff0000, v191
	v_lshlrev_b32_e32 v90, 16, v193
	v_and_b32_e32 v91, 0xffff0000, v193
	v_pk_fma_f32 v[84:85], v[84:85], v[104:105], v[96:97]
	v_pk_fma_f32 v[96:97], v[80:81], v[106:107], v[98:99]
	v_pk_fma_f32 v[86:87], v[86:87], v[88:89], v[100:101]
	v_pk_fma_f32 v[88:89], v[82:83], v[90:91], v[102:103]
	v_cvt_pk_bf16_f32 v80, v84, v85
	v_cvt_pk_bf16_f32 v81, v86, v87
	v_cvt_pk_bf16_f32 v82, v96, v97
	v_cvt_pk_bf16_f32 v83, v88, v89
	global_store_dwordx4 v[110:111], v[80:83], off offset:256
	s_add_u32 s98, s70, 0x80000
	s_addc_u32 s99, s71, 0
	s_add_u32 s100, s42, 0x40000
	s_addc_u32 s101, s43, 0
	global_load_dwordx4 v[176:179], v212, s[98:99] offset:2048
	global_load_dwordx4 v[182:185], v213, s[100:101]
	global_load_dwordx4 v[186:189], v213, s[100:101] offset:256
	global_load_dwordx4 v[190:193], v212, s[98:99] offset:2304
	s_waitcnt vmcnt(6)
	v_lshlrev_b32_e32 v96, 16, v194
	v_and_b32_e32 v97, 0xffff0000, v194
	v_lshlrev_b32_e32 v98, 16, v198
	v_and_b32_e32 v99, 0xffff0000, v198
	v_lshlrev_b32_e32 v100, 16, v196
	v_and_b32_e32 v101, 0xffff0000, v196
	v_lshlrev_b32_e32 v102, 16, v200
	v_and_b32_e32 v103, 0xffff0000, v200
	v_lshlrev_b32_e32 v80, 16, v195
	v_and_b32_e32 v81, 0xffff0000, v195
	v_lshlrev_b32_e32 v84, 16, v199
	v_and_b32_e32 v85, 0xffff0000, v199
	v_lshlrev_b32_e32 v82, 16, v197
	v_and_b32_e32 v83, 0xffff0000, v197
	v_lshlrev_b32_e32 v86, 16, v201
	v_and_b32_e32 v87, 0xffff0000, v201
	v_pk_fma_f32 v[76:77], v[76:77], v[96:97], v[98:99]
	v_pk_fma_f32 v[96:97], v[72:73], v[100:101], v[102:103]
	v_pk_fma_f32 v[78:79], v[78:79], v[80:81], v[84:85]
	v_pk_fma_f32 v[80:81], v[74:75], v[82:83], v[86:87]
	v_cvt_pk_bf16_f32 v72, v76, v77
	v_cvt_pk_bf16_f32 v73, v78, v79
	v_cvt_pk_bf16_f32 v74, v96, v97
	v_cvt_pk_bf16_f32 v75, v80, v81
	global_store_dwordx4 v[94:95], v[72:75], off
	v_add_u32_e32 v76, 0x80, v142
	v_lshlrev_b32_e32 v80, 16, v202
	v_and_b32_e32 v81, 0xffff0000, v202
	v_lshlrev_b32_e32 v82, 16, v204
	v_and_b32_e32 v83, 0xffff0000, v204
	v_lshlrev_b32_e32 v84, 16, v203
	v_and_b32_e32 v85, 0xffff0000, v203
	v_lshlrev_b32_e32 v86, 16, v205
	v_and_b32_e32 v87, 0xffff0000, v205
	v_ashrrev_i32_e32 v77, 31, v76
	v_lshlrev_b64 v[78:79], 11, v[76:77]
	v_lshlrev_b64 v[76:77], 12, v[76:77]
	v_lshl_add_u64 v[76:77], s[70:71], 0, v[76:77]
	v_lshl_add_u64 v[78:79], s[42:43], 0, v[78:79]
	v_lshl_add_u64 v[76:77], v[76:77], 0, v[140:141]
	v_lshl_add_u64 v[78:79], v[78:79], 0, v[140:141]
	v_lshlrev_b32_e32 v88, 16, v206
	v_and_b32_e32 v89, 0xffff0000, v206
	v_lshlrev_b32_e32 v90, 16, v208
	v_and_b32_e32 v91, 0xffff0000, v208
	v_lshlrev_b32_e32 v72, 16, v207
	v_and_b32_e32 v73, 0xffff0000, v207
	v_lshlrev_b32_e32 v74, 16, v209
	v_and_b32_e32 v75, 0xffff0000, v209
	v_pk_fma_f32 v[68:69], v[68:69], v[88:89], v[80:81]
	v_pk_fma_f32 v[80:81], v[64:65], v[90:91], v[82:83]
	v_pk_fma_f32 v[70:71], v[70:71], v[72:73], v[84:85]
	v_pk_fma_f32 v[72:73], v[66:67], v[74:75], v[86:87]
	v_cvt_pk_bf16_f32 v64, v68, v69
	v_cvt_pk_bf16_f32 v65, v70, v71
	v_cvt_pk_bf16_f32 v66, v80, v81
	v_cvt_pk_bf16_f32 v67, v72, v73
	global_store_dwordx4 v[94:95], v[64:67], off offset:256
	s_add_u32 s98, s70, 0x90000
	s_addc_u32 s99, s71, 0
	s_add_u32 s100, s42, 0x48000
	s_addc_u32 s101, s43, 0
	global_load_dwordx4 v[194:197], v212, s[98:99] offset:2048
	global_load_dwordx4 v[198:201], v213, s[100:101]
	global_load_dwordx4 v[202:205], v213, s[100:101] offset:256
	global_load_dwordx4 v[206:209], v212, s[98:99] offset:2304
	s_waitcnt vmcnt(6)
	v_lshlrev_b32_e32 v80, 16, v176
	v_and_b32_e32 v81, 0xffff0000, v176
	v_lshlrev_b32_e32 v82, 16, v182
	v_and_b32_e32 v83, 0xffff0000, v182
	v_lshlrev_b32_e32 v84, 16, v178
	v_and_b32_e32 v85, 0xffff0000, v178
	v_lshlrev_b32_e32 v86, 16, v184
	v_and_b32_e32 v87, 0xffff0000, v184
	v_lshlrev_b32_e32 v64, 16, v177
	v_and_b32_e32 v65, 0xffff0000, v177
	v_lshlrev_b32_e32 v68, 16, v183
	v_and_b32_e32 v69, 0xffff0000, v183
	v_lshlrev_b32_e32 v66, 16, v179
	v_and_b32_e32 v67, 0xffff0000, v179
	v_lshlrev_b32_e32 v70, 16, v185
	v_and_b32_e32 v71, 0xffff0000, v185
	v_pk_fma_f32 v[60:61], v[60:61], v[80:81], v[82:83]
	v_pk_fma_f32 v[80:81], v[56:57], v[84:85], v[86:87]
	v_pk_fma_f32 v[62:63], v[62:63], v[64:65], v[68:69]
	v_pk_fma_f32 v[64:65], v[58:59], v[66:67], v[70:71]
	v_cvt_pk_bf16_f32 v56, v60, v61
	v_cvt_pk_bf16_f32 v57, v62, v63
	v_cvt_pk_bf16_f32 v58, v80, v81
	v_cvt_pk_bf16_f32 v59, v64, v65
	global_store_dwordx4 v[78:79], v[56:59], off
	v_add_u32_e32 v60, 0x90, v142
	v_lshlrev_b32_e32 v64, 16, v186
	v_and_b32_e32 v65, 0xffff0000, v186
	v_lshlrev_b32_e32 v66, 16, v188
	v_and_b32_e32 v67, 0xffff0000, v188
	v_lshlrev_b32_e32 v68, 16, v187
	v_and_b32_e32 v69, 0xffff0000, v187
	v_lshlrev_b32_e32 v70, 16, v189
	v_and_b32_e32 v71, 0xffff0000, v189
	v_ashrrev_i32_e32 v61, 31, v60
	v_lshlrev_b64 v[62:63], 11, v[60:61]
	v_lshlrev_b64 v[60:61], 12, v[60:61]
	v_lshl_add_u64 v[60:61], s[70:71], 0, v[60:61]
	v_lshl_add_u64 v[62:63], s[42:43], 0, v[62:63]
	v_lshl_add_u64 v[60:61], v[60:61], 0, v[140:141]
	v_lshl_add_u64 v[62:63], v[62:63], 0, v[140:141]
	v_lshlrev_b32_e32 v72, 16, v190
	v_and_b32_e32 v73, 0xffff0000, v190
	v_lshlrev_b32_e32 v74, 16, v192
	v_and_b32_e32 v75, 0xffff0000, v192
	v_lshlrev_b32_e32 v56, 16, v191
	v_and_b32_e32 v57, 0xffff0000, v191
	v_lshlrev_b32_e32 v58, 16, v193
	v_and_b32_e32 v59, 0xffff0000, v193
	v_pk_fma_f32 v[52:53], v[52:53], v[72:73], v[64:65]
	v_pk_fma_f32 v[64:65], v[48:49], v[74:75], v[66:67]
	v_pk_fma_f32 v[54:55], v[54:55], v[56:57], v[68:69]
	v_pk_fma_f32 v[56:57], v[50:51], v[58:59], v[70:71]
	v_cvt_pk_bf16_f32 v48, v52, v53
	v_cvt_pk_bf16_f32 v49, v54, v55
	v_cvt_pk_bf16_f32 v50, v64, v65
	v_cvt_pk_bf16_f32 v51, v56, v57
	global_store_dwordx4 v[78:79], v[48:51], off offset:256
	s_add_u32 s98, s70, 0xa0000
	s_addc_u32 s99, s71, 0
	s_add_u32 s100, s42, 0x50000
	s_addc_u32 s101, s43, 0
	global_load_dwordx4 v[176:179], v212, s[98:99] offset:2048
	global_load_dwordx4 v[182:185], v213, s[100:101]
	global_load_dwordx4 v[186:189], v213, s[100:101] offset:256
	global_load_dwordx4 v[190:193], v212, s[98:99] offset:2304
	s_waitcnt vmcnt(6)
	v_lshlrev_b32_e32 v64, 16, v194
	v_and_b32_e32 v65, 0xffff0000, v194
	v_lshlrev_b32_e32 v66, 16, v198
	v_and_b32_e32 v67, 0xffff0000, v198
	v_lshlrev_b32_e32 v68, 16, v196
	v_and_b32_e32 v69, 0xffff0000, v196
	v_lshlrev_b32_e32 v70, 16, v200
	v_and_b32_e32 v71, 0xffff0000, v200
	v_lshlrev_b32_e32 v48, 16, v195
	v_and_b32_e32 v49, 0xffff0000, v195
	v_lshlrev_b32_e32 v52, 16, v199
	v_and_b32_e32 v53, 0xffff0000, v199
	v_lshlrev_b32_e32 v50, 16, v197
	v_and_b32_e32 v51, 0xffff0000, v197
	v_lshlrev_b32_e32 v54, 16, v201
	v_and_b32_e32 v55, 0xffff0000, v201
	v_pk_fma_f32 v[44:45], v[44:45], v[64:65], v[66:67]
	v_pk_fma_f32 v[64:65], v[40:41], v[68:69], v[70:71]
	v_pk_fma_f32 v[46:47], v[46:47], v[48:49], v[52:53]
	v_pk_fma_f32 v[48:49], v[42:43], v[50:51], v[54:55]
	v_cvt_pk_bf16_f32 v40, v44, v45
	v_cvt_pk_bf16_f32 v41, v46, v47
	v_cvt_pk_bf16_f32 v42, v64, v65
	v_cvt_pk_bf16_f32 v43, v48, v49
	global_store_dwordx4 v[62:63], v[40:43], off
	v_add_u32_e32 v44, 0xa0, v142
	v_lshlrev_b32_e32 v48, 16, v202
	v_and_b32_e32 v49, 0xffff0000, v202
	v_lshlrev_b32_e32 v50, 16, v204
	v_and_b32_e32 v51, 0xffff0000, v204
	v_lshlrev_b32_e32 v52, 16, v203
	v_and_b32_e32 v53, 0xffff0000, v203
	v_lshlrev_b32_e32 v54, 16, v205
	v_and_b32_e32 v55, 0xffff0000, v205
	v_ashrrev_i32_e32 v45, 31, v44
	v_lshlrev_b64 v[46:47], 11, v[44:45]
	v_lshlrev_b64 v[44:45], 12, v[44:45]
	v_lshl_add_u64 v[44:45], s[70:71], 0, v[44:45]
	v_lshl_add_u64 v[46:47], s[42:43], 0, v[46:47]
	v_lshl_add_u64 v[44:45], v[44:45], 0, v[140:141]
	v_lshl_add_u64 v[46:47], v[46:47], 0, v[140:141]
	v_lshlrev_b32_e32 v56, 16, v206
	v_and_b32_e32 v57, 0xffff0000, v206
	v_lshlrev_b32_e32 v58, 16, v208
	v_and_b32_e32 v59, 0xffff0000, v208
	v_lshlrev_b32_e32 v40, 16, v207
	v_and_b32_e32 v41, 0xffff0000, v207
	v_lshlrev_b32_e32 v42, 16, v209
	v_and_b32_e32 v43, 0xffff0000, v209
	v_pk_fma_f32 v[36:37], v[36:37], v[56:57], v[48:49]
	v_pk_fma_f32 v[48:49], v[32:33], v[58:59], v[50:51]
	v_pk_fma_f32 v[38:39], v[38:39], v[40:41], v[52:53]
	v_pk_fma_f32 v[40:41], v[34:35], v[42:43], v[54:55]
	v_cvt_pk_bf16_f32 v32, v36, v37
	v_cvt_pk_bf16_f32 v33, v38, v39
	v_cvt_pk_bf16_f32 v34, v48, v49
	v_cvt_pk_bf16_f32 v35, v40, v41
	global_store_dwordx4 v[62:63], v[32:35], off offset:256
	s_add_u32 s98, s70, 0xb0000
	s_addc_u32 s99, s71, 0
	s_add_u32 s100, s42, 0x58000
	s_addc_u32 s101, s43, 0
	global_load_dwordx4 v[194:197], v212, s[98:99] offset:2048
	global_load_dwordx4 v[198:201], v213, s[100:101]
	global_load_dwordx4 v[202:205], v213, s[100:101] offset:256
	global_load_dwordx4 v[206:209], v212, s[98:99] offset:2304
	s_waitcnt vmcnt(6)
	v_lshlrev_b32_e32 v48, 16, v176
	v_and_b32_e32 v49, 0xffff0000, v176
	v_lshlrev_b32_e32 v50, 16, v182
	v_and_b32_e32 v51, 0xffff0000, v182
	v_lshlrev_b32_e32 v52, 16, v178
	v_and_b32_e32 v53, 0xffff0000, v178
	v_lshlrev_b32_e32 v54, 16, v184
	v_and_b32_e32 v55, 0xffff0000, v184
	v_lshlrev_b32_e32 v32, 16, v177
	v_and_b32_e32 v33, 0xffff0000, v177
	v_lshlrev_b32_e32 v36, 16, v183
	v_and_b32_e32 v37, 0xffff0000, v183
	v_lshlrev_b32_e32 v34, 16, v179
	v_and_b32_e32 v35, 0xffff0000, v179
	v_lshlrev_b32_e32 v38, 16, v185
	v_and_b32_e32 v39, 0xffff0000, v185
	v_pk_fma_f32 v[28:29], v[28:29], v[48:49], v[50:51]
	v_pk_fma_f32 v[48:49], v[24:25], v[52:53], v[54:55]
	v_pk_fma_f32 v[30:31], v[30:31], v[32:33], v[36:37]
	v_pk_fma_f32 v[32:33], v[26:27], v[34:35], v[38:39]
	v_cvt_pk_bf16_f32 v24, v28, v29
	v_cvt_pk_bf16_f32 v25, v30, v31
	v_cvt_pk_bf16_f32 v26, v48, v49
	v_cvt_pk_bf16_f32 v27, v32, v33
	global_store_dwordx4 v[46:47], v[24:27], off
	v_add_u32_e32 v28, 0xb0, v142
	v_lshlrev_b32_e32 v32, 16, v186
	v_and_b32_e32 v33, 0xffff0000, v186
	v_lshlrev_b32_e32 v34, 16, v188
	v_and_b32_e32 v35, 0xffff0000, v188
	v_lshlrev_b32_e32 v36, 16, v187
	v_and_b32_e32 v37, 0xffff0000, v187
	v_lshlrev_b32_e32 v38, 16, v189
	v_and_b32_e32 v39, 0xffff0000, v189
	v_ashrrev_i32_e32 v29, 31, v28
	v_lshlrev_b64 v[30:31], 11, v[28:29]
	v_lshlrev_b64 v[28:29], 12, v[28:29]
	v_lshl_add_u64 v[28:29], s[70:71], 0, v[28:29]
	v_lshl_add_u64 v[30:31], s[42:43], 0, v[30:31]
	v_lshl_add_u64 v[28:29], v[28:29], 0, v[140:141]
	v_lshl_add_u64 v[30:31], v[30:31], 0, v[140:141]
	v_lshlrev_b32_e32 v40, 16, v190
	v_and_b32_e32 v41, 0xffff0000, v190
	v_lshlrev_b32_e32 v42, 16, v192
	v_and_b32_e32 v43, 0xffff0000, v192
	v_lshlrev_b32_e32 v24, 16, v191
	v_and_b32_e32 v25, 0xffff0000, v191
	v_lshlrev_b32_e32 v26, 16, v193
	v_and_b32_e32 v27, 0xffff0000, v193
	v_pk_fma_f32 v[20:21], v[20:21], v[40:41], v[32:33]
	v_pk_fma_f32 v[32:33], v[16:17], v[42:43], v[34:35]
	v_pk_fma_f32 v[22:23], v[22:23], v[24:25], v[36:37]
	v_pk_fma_f32 v[24:25], v[18:19], v[26:27], v[38:39]
	v_cvt_pk_bf16_f32 v16, v20, v21
	v_cvt_pk_bf16_f32 v17, v22, v23
	v_cvt_pk_bf16_f32 v18, v32, v33
	v_cvt_pk_bf16_f32 v19, v24, v25
	global_store_dwordx4 v[46:47], v[16:19], off offset:256
	s_waitcnt vmcnt(2)
	v_lshlrev_b32_e32 v32, 16, v194
	v_and_b32_e32 v33, 0xffff0000, v194
	v_lshlrev_b32_e32 v34, 16, v198
	v_and_b32_e32 v35, 0xffff0000, v198
	v_lshlrev_b32_e32 v36, 16, v196
	v_and_b32_e32 v37, 0xffff0000, v196
	v_lshlrev_b32_e32 v38, 16, v200
	v_and_b32_e32 v39, 0xffff0000, v200
	v_lshlrev_b32_e32 v16, 16, v195
	v_and_b32_e32 v17, 0xffff0000, v195
	v_lshlrev_b32_e32 v20, 16, v199
	v_and_b32_e32 v21, 0xffff0000, v199
	v_lshlrev_b32_e32 v18, 16, v197
	v_and_b32_e32 v19, 0xffff0000, v197
	v_lshlrev_b32_e32 v22, 16, v201
	v_and_b32_e32 v23, 0xffff0000, v201
	v_pk_fma_f32 v[12:13], v[12:13], v[32:33], v[34:35]
	v_pk_fma_f32 v[32:33], v[8:9], v[36:37], v[38:39]
	v_pk_fma_f32 v[14:15], v[14:15], v[16:17], v[20:21]
	v_pk_fma_f32 v[16:17], v[10:11], v[18:19], v[22:23]
	v_cvt_pk_bf16_f32 v8, v12, v13
	v_cvt_pk_bf16_f32 v9, v14, v15
	v_cvt_pk_bf16_f32 v10, v32, v33
	v_cvt_pk_bf16_f32 v11, v16, v17
	global_store_dwordx4 v[30:31], v[8:11], off
	v_lshlrev_b32_e32 v12, 16, v202
	v_and_b32_e32 v13, 0xffff0000, v202
	v_lshlrev_b32_e32 v14, 16, v204
	v_and_b32_e32 v15, 0xffff0000, v204
	v_lshlrev_b32_e32 v16, 16, v203
	v_and_b32_e32 v17, 0xffff0000, v203
	v_lshlrev_b32_e32 v18, 16, v205
	v_and_b32_e32 v19, 0xffff0000, v205
	v_lshlrev_b32_e32 v20, 16, v206
	v_and_b32_e32 v21, 0xffff0000, v206
	v_lshlrev_b32_e32 v22, 16, v208
	v_and_b32_e32 v23, 0xffff0000, v208
	v_lshlrev_b32_e32 v8, 16, v207
	v_and_b32_e32 v9, 0xffff0000, v207
	v_lshlrev_b32_e32 v10, 16, v209
	v_and_b32_e32 v11, 0xffff0000, v209
	v_pk_fma_f32 v[4:5], v[4:5], v[20:21], v[12:13]
	v_pk_fma_f32 v[12:13], v[0:1], v[22:23], v[14:15]
	v_pk_fma_f32 v[6:7], v[6:7], v[8:9], v[16:17]
	v_pk_fma_f32 v[8:9], v[2:3], v[10:11], v[18:19]
	v_cvt_pk_bf16_f32 v0, v4, v5
	v_cvt_pk_bf16_f32 v1, v6, v7
	v_cvt_pk_bf16_f32 v2, v12, v13
	v_cvt_pk_bf16_f32 v3, v8, v9
	global_store_dwordx4 v[30:31], v[0:3], off offset:256
	s_cbranch_vccnz .LBB0_807
	s_andn2_b64 vcc, exec, s[4:5]
	s_cbranch_vccnz .LBB0_806
	s_barrier
	s_branch .LBB0_806

.LBB0_1143:
	v_lshl_add_u32 v146, s54, 8, v157
	v_ashrrev_i32_e32 v147, 31, v146
	v_lshl_or_b32 v144, s20, 8, v159
	v_lshlrev_b64 v[164:165], 11, v[146:147]
	v_ashrrev_i32_e32 v145, 31, v144
	v_lshl_add_u64 v[164:165], s[40:41], 0, v[164:165]
	v_lshl_add_u64 v[174:175], v[144:145], 1, v[164:165]
	v_lshlrev_b32_e32 v224, 11, v146
	v_lshl_add_u32 v224, v144, 1, v224
	s_add_u32 s98, s40, 0x0
	s_addc_u32 s99, s41, 0
	global_load_dwordx4 v[186:189], v224, s[98:99]
	global_load_dwordx4 v[190:193], v224, s[98:99] offset:256
	s_add_u32 s98, s40, 0x8000
	s_addc_u32 s99, s41, 0
	global_load_dwordx4 v[194:197], v224, s[98:99]
	global_load_dwordx4 v[198:201], v224, s[98:99] offset:256
	s_add_u32 s98, s40, 0x10000
	s_addc_u32 s99, s41, 0
	global_load_dwordx4 v[202:205], v224, s[98:99]
	global_load_dwordx4 v[206:209], v224, s[98:99] offset:256
	s_add_u32 s98, s40, 0x18000
	s_addc_u32 s99, s41, 0
	global_load_dwordx4 v[212:215], v224, s[98:99]
	global_load_dwordx4 v[216:219], v224, s[98:99] offset:256
	v_and_b32_e32 v165, 64, v163
	v_xor_b32_e32 v164, 16, v163
	v_add_u32_e32 v165, 64, v165
	v_xor_b32_e32 v176, 32, v163
	v_cmp_lt_i32_e32 vcc, v164, v165
	s_lshl_b32 s30, s20, 2
	s_ashr_i32 s31, s30, 31
	v_cndmask_b32_e32 v164, v163, v164, vcc
	v_cmp_lt_i32_e32 vcc, v176, v165
	v_lshlrev_b32_e32 v165, 2, v164
	s_waitcnt vmcnt(6)
	v_and_b32_e32 v177, 0xffff0000, v186
	v_cndmask_b32_e32 v176, v163, v176, vcc
	v_lshlrev_b32_e32 v164, 2, v176
	v_lshlrev_b32_e32 v176, 16, v186
	v_lshlrev_b32_e32 v178, 16, v188
	v_and_b32_e32 v179, 0xffff0000, v188
	v_lshlrev_b32_e32 v166, 16, v187
	v_and_b32_e32 v167, 0xffff0000, v187
	v_lshlrev_b32_e32 v168, 16, v189
	v_and_b32_e32 v169, 0xffff0000, v189
	v_lshlrev_b32_e32 v182, 16, v190
	v_and_b32_e32 v183, 0xffff0000, v190
	v_lshlrev_b32_e32 v184, 16, v192
	v_and_b32_e32 v185, 0xffff0000, v192
	v_lshlrev_b32_e32 v170, 16, v191
	v_and_b32_e32 v171, 0xffff0000, v191
	v_lshlrev_b32_e32 v172, 16, v193
	v_and_b32_e32 v173, 0xffff0000, v193
	v_pk_add_f32 v[124:125], v[124:125], v[176:177]
	v_pk_add_f32 v[120:121], v[120:121], v[178:179]
	v_pk_add_f32 v[126:127], v[126:127], v[166:167]
	v_pk_add_f32 v[122:123], v[122:123], v[168:169]
	v_pk_add_f32 v[116:117], v[116:117], v[182:183]
	v_pk_add_f32 v[166:167], v[112:113], v[184:185]
	v_pk_add_f32 v[118:119], v[118:119], v[170:171]
	v_pk_add_f32 v[168:169], v[114:115], v[172:173]
	v_cvt_pk_bf16_f32 v112, v124, v125
	v_cvt_pk_bf16_f32 v113, v126, v127
	v_pk_mul_f32 v[114:115], v[124:125], v[124:125]
	v_pk_mul_f32 v[124:125], v[126:127], v[126:127]
	v_pk_mul_f32 v[126:127], v[120:121], v[120:121]
	v_pk_mul_f32 v[170:171], v[122:123], v[122:123]
	v_pk_mul_f32 v[172:173], v[116:117], v[116:117]
	v_pk_mul_f32 v[176:177], v[118:119], v[118:119]
	v_pk_mul_f32 v[178:179], v[166:167], v[166:167]
	v_pk_mul_f32 v[182:183], v[168:169], v[168:169]
	v_add_f32_e32 v178, v178, v179
	v_add_f32_e32 v180, v182, v183
	v_add_f32_e32 v176, v176, v177
	v_add_f32_e32 v172, v172, v173
	v_add_f32_e32 v170, v170, v171
	v_add_f32_e32 v126, v126, v127
	v_add_f32_e32 v124, v124, v125
	v_add_f32_e32 v114, v114, v115
	v_add_f32_e32 v115, v178, v180
	v_add_f32_e32 v125, v172, v176
	v_add_f32_e32 v126, v126, v170
	v_add_f32_e32 v114, v114, v124
	v_add_f32_e32 v115, v125, v115
	v_add_f32_e32 v114, v114, v126
	v_add_f32_e32 v124, v114, v115
	ds_bpermute_b32 v125, v165, v124
	v_cvt_pk_bf16_f32 v114, v120, v121
	v_cvt_pk_bf16_f32 v115, v122, v123
	global_store_dwordx4 v[174:175], v[112:115], off
	s_waitcnt lgkmcnt(0)
	s_nop 0
	v_add_f32_e32 v112, v124, v125
	ds_bpermute_b32 v113, v164, v112
	v_cvt_pk_bf16_f32 v114, v116, v117
	v_cvt_pk_bf16_f32 v115, v118, v119
	v_cvt_pk_bf16_f32 v116, v166, v167
	v_cvt_pk_bf16_f32 v117, v168, v169
	global_store_dwordx4 v[174:175], v[114:117], off offset:256
	s_add_u32 s98, s40, 0x40000
	s_addc_u32 s99, s41, 0
	global_load_dwordx4 v[186:189], v224, s[98:99]
	global_load_dwordx4 v[190:193], v224, s[98:99] offset:256
	s_and_saveexec_b64 s[34:35], s[2:3]
	s_cbranch_execz .LBB0_1145
	v_lshlrev_b64 v[114:115], 6, v[146:147]
	v_lshl_add_u64 v[114:115], s[12:13], 0, v[114:115]
	v_lshl_add_u64 v[114:115], s[30:31], 2, v[114:115]
	s_lshl_b32 s20, s44, 2
	v_lshl_add_u64 v[114:115], v[114:115], 0, s[20:21]
	s_waitcnt lgkmcnt(0)
	v_add_f32_e32 v112, v112, v113
	global_store_dword v[114:115], v112, off
.LBB0_1145:
	s_or_b64 exec, exec, s[34:35]
	v_or_b32_e32 v112, 16, v146
	s_waitcnt lgkmcnt(0)
	v_ashrrev_i32_e32 v113, 31, v112
	v_lshlrev_b64 v[114:115], 11, v[112:113]
	v_lshl_add_u64 v[114:115], s[40:41], 0, v[114:115]
	v_lshl_add_u64 v[122:123], v[144:145], 1, v[114:115]
	s_waitcnt vmcnt(8)
	v_lshlrev_b32_e32 v124, 16, v194
	v_and_b32_e32 v125, 0xffff0000, v194
	v_lshlrev_b32_e32 v126, 16, v196
	v_and_b32_e32 v127, 0xffff0000, v196
	v_lshlrev_b32_e32 v114, 16, v195
	v_and_b32_e32 v115, 0xffff0000, v195
	v_lshlrev_b32_e32 v116, 16, v197
	v_and_b32_e32 v117, 0xffff0000, v197
	v_lshlrev_b32_e32 v166, 16, v198
	v_and_b32_e32 v167, 0xffff0000, v198
	v_lshlrev_b32_e32 v168, 16, v200
	v_and_b32_e32 v169, 0xffff0000, v200
	v_lshlrev_b32_e32 v118, 16, v199
	v_and_b32_e32 v119, 0xffff0000, v199
	v_lshlrev_b32_e32 v120, 16, v201
	v_and_b32_e32 v121, 0xffff0000, v201
	v_pk_add_f32 v[108:109], v[108:109], v[124:125]
	v_pk_add_f32 v[104:105], v[104:105], v[126:127]
	v_pk_add_f32 v[110:111], v[110:111], v[114:115]
	v_pk_add_f32 v[106:107], v[106:107], v[116:117]
	v_pk_add_f32 v[100:101], v[100:101], v[166:167]
	v_pk_add_f32 v[114:115], v[96:97], v[168:169]
	v_pk_add_f32 v[102:103], v[102:103], v[118:119]
	v_pk_add_f32 v[116:117], v[98:99], v[120:121]
	v_cvt_pk_bf16_f32 v96, v108, v109
	v_cvt_pk_bf16_f32 v97, v110, v111
	v_pk_mul_f32 v[98:99], v[108:109], v[108:109]
	v_pk_mul_f32 v[108:109], v[110:111], v[110:111]
	v_pk_mul_f32 v[110:111], v[104:105], v[104:105]
	v_pk_mul_f32 v[118:119], v[106:107], v[106:107]
	v_pk_mul_f32 v[120:121], v[100:101], v[100:101]
	v_pk_mul_f32 v[124:125], v[102:103], v[102:103]
	v_pk_mul_f32 v[126:127], v[114:115], v[114:115]
	v_pk_mul_f32 v[166:167], v[116:117], v[116:117]
	v_add_f32_e32 v126, v126, v127
	v_add_f32_e32 v147, v166, v167
	v_add_f32_e32 v124, v124, v125
	v_add_f32_e32 v120, v120, v121
	v_add_f32_e32 v118, v118, v119
	v_add_f32_e32 v110, v110, v111
	v_add_f32_e32 v108, v108, v109
	v_add_f32_e32 v98, v98, v99
	v_add_f32_e32 v99, v126, v147
	v_add_f32_e32 v109, v120, v124
	v_add_f32_e32 v110, v110, v118
	v_add_f32_e32 v98, v98, v108
	v_add_f32_e32 v99, v109, v99
	v_add_f32_e32 v98, v98, v110
	v_add_f32_e32 v108, v98, v99
	ds_bpermute_b32 v109, v165, v108
	v_cvt_pk_bf16_f32 v98, v104, v105
	v_cvt_pk_bf16_f32 v99, v106, v107
	global_store_dwordx4 v[122:123], v[96:99], off
	s_waitcnt lgkmcnt(0)
	s_nop 0
	v_add_f32_e32 v96, v108, v109
	ds_bpermute_b32 v97, v164, v96
	v_cvt_pk_bf16_f32 v98, v100, v101
	v_cvt_pk_bf16_f32 v99, v102, v103
	v_cvt_pk_bf16_f32 v100, v114, v115
	v_cvt_pk_bf16_f32 v101, v116, v117
	global_store_dwordx4 v[122:123], v[98:101], off offset:256
	s_add_u32 s98, s40, 0x48000
	s_addc_u32 s99, s41, 0
	global_load_dwordx4 v[194:197], v224, s[98:99]
	global_load_dwordx4 v[198:201], v224, s[98:99] offset:256
	s_and_saveexec_b64 s[34:35], s[2:3]
	s_cbranch_execz .LBB0_1147
	v_lshlrev_b64 v[98:99], 6, v[112:113]
	v_lshl_add_u64 v[98:99], s[12:13], 0, v[98:99]
	v_lshl_add_u64 v[98:99], s[30:31], 2, v[98:99]
	s_lshl_b32 s20, s44, 2
	v_lshl_add_u64 v[98:99], v[98:99], 0, s[20:21]
	s_waitcnt lgkmcnt(0)
	v_add_f32_e32 v96, v96, v97
	global_store_dword v[98:99], v96, off
.LBB0_1147:
	s_or_b64 exec, exec, s[34:35]
	v_or_b32_e32 v96, 32, v146
	s_waitcnt lgkmcnt(0)
	v_ashrrev_i32_e32 v97, 31, v96
	v_lshlrev_b64 v[98:99], 11, v[96:97]
	v_lshl_add_u64 v[98:99], s[40:41], 0, v[98:99]
	v_lshl_add_u64 v[106:107], v[144:145], 1, v[98:99]
	s_waitcnt vmcnt(10)
	v_lshlrev_b32_e32 v108, 16, v202
	v_and_b32_e32 v109, 0xffff0000, v202
	v_lshlrev_b32_e32 v110, 16, v204
	v_and_b32_e32 v111, 0xffff0000, v204
	v_lshlrev_b32_e32 v98, 16, v203
	v_and_b32_e32 v99, 0xffff0000, v203
	v_lshlrev_b32_e32 v100, 16, v205
	v_and_b32_e32 v101, 0xffff0000, v205
	v_lshlrev_b32_e32 v112, 16, v206
	v_and_b32_e32 v113, 0xffff0000, v206
	v_lshlrev_b32_e32 v114, 16, v208
	v_and_b32_e32 v115, 0xffff0000, v208
	v_lshlrev_b32_e32 v102, 16, v207
	v_and_b32_e32 v103, 0xffff0000, v207
	v_lshlrev_b32_e32 v104, 16, v209
	v_and_b32_e32 v105, 0xffff0000, v209
	v_pk_add_f32 v[92:93], v[92:93], v[108:109]
	v_pk_add_f32 v[88:89], v[88:89], v[110:111]
	v_pk_add_f32 v[94:95], v[94:95], v[98:99]
	v_pk_add_f32 v[90:91], v[90:91], v[100:101]
	v_pk_add_f32 v[84:85], v[84:85], v[112:113]
	v_pk_add_f32 v[98:99], v[80:81], v[114:115]
	v_pk_add_f32 v[86:87], v[86:87], v[102:103]
	v_pk_add_f32 v[100:101], v[82:83], v[104:105]
	v_cvt_pk_bf16_f32 v80, v92, v93
	v_cvt_pk_bf16_f32 v81, v94, v95
	v_pk_mul_f32 v[82:83], v[92:93], v[92:93]
	v_pk_mul_f32 v[92:93], v[94:95], v[94:95]
	v_pk_mul_f32 v[94:95], v[88:89], v[88:89]
	v_pk_mul_f32 v[102:103], v[90:91], v[90:91]
	v_pk_mul_f32 v[104:105], v[84:85], v[84:85]
	v_pk_mul_f32 v[108:109], v[86:87], v[86:87]
	v_pk_mul_f32 v[110:111], v[98:99], v[98:99]
	v_pk_mul_f32 v[112:113], v[100:101], v[100:101]
	v_add_f32_e32 v110, v110, v111
	v_add_f32_e32 v112, v112, v113
	v_add_f32_e32 v108, v108, v109
	v_add_f32_e32 v104, v104, v105
	v_add_f32_e32 v102, v102, v103
	v_add_f32_e32 v94, v94, v95
	v_add_f32_e32 v92, v92, v93
	v_add_f32_e32 v82, v82, v83
	v_add_f32_e32 v83, v110, v112
	v_add_f32_e32 v93, v104, v108
	v_add_f32_e32 v94, v94, v102
	v_add_f32_e32 v82, v82, v92
	v_add_f32_e32 v83, v93, v83
	v_add_f32_e32 v82, v82, v94
	v_add_f32_e32 v92, v82, v83
	ds_bpermute_b32 v93, v165, v92
	v_cvt_pk_bf16_f32 v82, v88, v89
	v_cvt_pk_bf16_f32 v83, v90, v91
	global_store_dwordx4 v[106:107], v[80:83], off
	s_waitcnt lgkmcnt(0)
	s_nop 0
	v_add_f32_e32 v80, v92, v93
	ds_bpermute_b32 v81, v164, v80
	v_cvt_pk_bf16_f32 v82, v84, v85
	v_cvt_pk_bf16_f32 v83, v86, v87
	v_cvt_pk_bf16_f32 v84, v98, v99
	v_cvt_pk_bf16_f32 v85, v100, v101
	global_store_dwordx4 v[106:107], v[82:85], off offset:256
	s_add_u32 s98, s40, 0x50000
	s_addc_u32 s99, s41, 0
	global_load_dwordx4 v[202:205], v224, s[98:99]
	global_load_dwordx4 v[206:209], v224, s[98:99] offset:256
	s_and_saveexec_b64 s[34:35], s[2:3]
	s_cbranch_execz .LBB0_1149
	v_lshlrev_b64 v[82:83], 6, v[96:97]
	v_lshl_add_u64 v[82:83], s[12:13], 0, v[82:83]
	v_lshl_add_u64 v[82:83], s[30:31], 2, v[82:83]
	s_lshl_b32 s20, s44, 2
	v_lshl_add_u64 v[82:83], v[82:83], 0, s[20:21]
	s_waitcnt lgkmcnt(0)
	v_add_f32_e32 v80, v80, v81
	global_store_dword v[82:83], v80, off
.LBB0_1149:
	s_or_b64 exec, exec, s[34:35]
	v_or_b32_e32 v80, 48, v146
	s_waitcnt lgkmcnt(0)
	v_ashrrev_i32_e32 v81, 31, v80
	v_lshlrev_b64 v[82:83], 11, v[80:81]
	v_lshl_add_u64 v[82:83], s[40:41], 0, v[82:83]
	v_lshl_add_u64 v[90:91], v[144:145], 1, v[82:83]
	s_waitcnt vmcnt(12)
	v_lshlrev_b32_e32 v92, 16, v212
	v_and_b32_e32 v93, 0xffff0000, v212
	v_lshlrev_b32_e32 v94, 16, v214
	v_and_b32_e32 v95, 0xffff0000, v214
	v_lshlrev_b32_e32 v82, 16, v213
	v_and_b32_e32 v83, 0xffff0000, v213
	v_lshlrev_b32_e32 v84, 16, v215
	v_and_b32_e32 v85, 0xffff0000, v215
	v_lshlrev_b32_e32 v96, 16, v216
	v_and_b32_e32 v97, 0xffff0000, v216
	v_lshlrev_b32_e32 v98, 16, v218
	v_and_b32_e32 v99, 0xffff0000, v218
	v_lshlrev_b32_e32 v86, 16, v217
	v_and_b32_e32 v87, 0xffff0000, v217
	v_lshlrev_b32_e32 v88, 16, v219
	v_and_b32_e32 v89, 0xffff0000, v219
	v_pk_add_f32 v[76:77], v[76:77], v[92:93]
	v_pk_add_f32 v[72:73], v[72:73], v[94:95]
	v_pk_add_f32 v[78:79], v[78:79], v[82:83]
	v_pk_add_f32 v[74:75], v[74:75], v[84:85]
	v_pk_add_f32 v[68:69], v[68:69], v[96:97]
	v_pk_add_f32 v[82:83], v[64:65], v[98:99]
	v_pk_add_f32 v[70:71], v[70:71], v[86:87]
	v_pk_add_f32 v[84:85], v[66:67], v[88:89]
	v_cvt_pk_bf16_f32 v64, v76, v77
	v_cvt_pk_bf16_f32 v65, v78, v79
	v_pk_mul_f32 v[66:67], v[76:77], v[76:77]
	v_pk_mul_f32 v[76:77], v[78:79], v[78:79]
	v_pk_mul_f32 v[78:79], v[72:73], v[72:73]
	v_pk_mul_f32 v[86:87], v[74:75], v[74:75]
	v_pk_mul_f32 v[88:89], v[68:69], v[68:69]
	v_pk_mul_f32 v[92:93], v[70:71], v[70:71]
	v_pk_mul_f32 v[94:95], v[82:83], v[82:83]
	v_pk_mul_f32 v[96:97], v[84:85], v[84:85]
	v_add_f32_e32 v94, v94, v95
	v_add_f32_e32 v96, v96, v97
	v_add_f32_e32 v92, v92, v93
	v_add_f32_e32 v88, v88, v89
	v_add_f32_e32 v86, v86, v87
	v_add_f32_e32 v78, v78, v79
	v_add_f32_e32 v76, v76, v77
	v_add_f32_e32 v66, v66, v67
	v_add_f32_e32 v67, v94, v96
	v_add_f32_e32 v77, v88, v92
	v_add_f32_e32 v78, v78, v86
	v_add_f32_e32 v66, v66, v76
	v_add_f32_e32 v67, v77, v67
	v_add_f32_e32 v66, v66, v78
	v_add_f32_e32 v76, v66, v67
	ds_bpermute_b32 v77, v165, v76
	v_cvt_pk_bf16_f32 v66, v72, v73
	v_cvt_pk_bf16_f32 v67, v74, v75
	global_store_dwordx4 v[90:91], v[64:67], off
	s_waitcnt lgkmcnt(0)
	s_nop 0
	v_add_f32_e32 v64, v76, v77
	ds_bpermute_b32 v65, v164, v64
	v_cvt_pk_bf16_f32 v66, v68, v69
	v_cvt_pk_bf16_f32 v67, v70, v71
	v_cvt_pk_bf16_f32 v68, v82, v83
	v_cvt_pk_bf16_f32 v69, v84, v85
	global_store_dwordx4 v[90:91], v[66:69], off offset:256
	s_add_u32 s98, s40, 0x58000
	s_addc_u32 s99, s41, 0
	global_load_dwordx4 v[212:215], v224, s[98:99]
	global_load_dwordx4 v[216:219], v224, s[98:99] offset:256
	s_and_saveexec_b64 s[34:35], s[2:3]
	s_cbranch_execz .LBB0_1151
	v_lshlrev_b64 v[66:67], 6, v[80:81]
	v_lshl_add_u64 v[66:67], s[12:13], 0, v[66:67]
	v_lshl_add_u64 v[66:67], s[30:31], 2, v[66:67]
	s_lshl_b32 s20, s44, 2
	v_lshl_add_u64 v[66:67], v[66:67], 0, s[20:21]
	s_waitcnt lgkmcnt(0)
	v_add_f32_e32 v64, v64, v65
	global_store_dword v[66:67], v64, off
.LBB0_1151:
	s_or_b64 exec, exec, s[34:35]
	v_add_u32_e32 v64, 0x80, v146
	s_waitcnt lgkmcnt(0)
	v_ashrrev_i32_e32 v65, 31, v64
	v_lshlrev_b64 v[66:67], 11, v[64:65]
	v_lshl_add_u64 v[66:67], s[40:41], 0, v[66:67]
	v_lshl_add_u64 v[74:75], v[144:145], 1, v[66:67]
	s_waitcnt vmcnt(12)
	v_lshlrev_b32_e32 v76, 16, v186
	v_and_b32_e32 v77, 0xffff0000, v186
	v_lshlrev_b32_e32 v78, 16, v188
	v_and_b32_e32 v79, 0xffff0000, v188
	v_lshlrev_b32_e32 v66, 16, v187
	v_and_b32_e32 v67, 0xffff0000, v187
	v_lshlrev_b32_e32 v68, 16, v189
	v_and_b32_e32 v69, 0xffff0000, v189
	v_lshlrev_b32_e32 v80, 16, v190
	v_and_b32_e32 v81, 0xffff0000, v190
	v_lshlrev_b32_e32 v82, 16, v192
	v_and_b32_e32 v83, 0xffff0000, v192
	v_lshlrev_b32_e32 v70, 16, v191
	v_and_b32_e32 v71, 0xffff0000, v191
	v_lshlrev_b32_e32 v72, 16, v193
	v_and_b32_e32 v73, 0xffff0000, v193
	v_pk_add_f32 v[60:61], v[60:61], v[76:77]
	v_pk_add_f32 v[56:57], v[56:57], v[78:79]
	v_pk_add_f32 v[62:63], v[62:63], v[66:67]
	v_pk_add_f32 v[58:59], v[58:59], v[68:69]
	v_pk_add_f32 v[52:53], v[52:53], v[80:81]
	v_pk_add_f32 v[66:67], v[48:49], v[82:83]
	v_pk_add_f32 v[54:55], v[54:55], v[70:71]
	v_pk_add_f32 v[68:69], v[50:51], v[72:73]
	v_cvt_pk_bf16_f32 v48, v60, v61
	v_cvt_pk_bf16_f32 v49, v62, v63
	v_pk_mul_f32 v[50:51], v[60:61], v[60:61]
	v_pk_mul_f32 v[60:61], v[62:63], v[62:63]
	v_pk_mul_f32 v[62:63], v[56:57], v[56:57]
	v_pk_mul_f32 v[70:71], v[58:59], v[58:59]
	v_pk_mul_f32 v[72:73], v[52:53], v[52:53]
	v_pk_mul_f32 v[76:77], v[54:55], v[54:55]
	v_pk_mul_f32 v[78:79], v[66:67], v[66:67]
	v_pk_mul_f32 v[80:81], v[68:69], v[68:69]
	v_add_f32_e32 v78, v78, v79
	v_add_f32_e32 v80, v80, v81
	v_add_f32_e32 v76, v76, v77
	v_add_f32_e32 v72, v72, v73
	v_add_f32_e32 v70, v70, v71
	v_add_f32_e32 v62, v62, v63
	v_add_f32_e32 v60, v60, v61
	v_add_f32_e32 v50, v50, v51
	v_add_f32_e32 v51, v78, v80
	v_add_f32_e32 v61, v72, v76
	v_add_f32_e32 v62, v62, v70
	v_add_f32_e32 v50, v50, v60
	v_add_f32_e32 v51, v61, v51
	v_add_f32_e32 v50, v50, v62
	v_add_f32_e32 v60, v50, v51
	ds_bpermute_b32 v61, v165, v60
	v_cvt_pk_bf16_f32 v50, v56, v57
	v_cvt_pk_bf16_f32 v51, v58, v59
	global_store_dwordx4 v[74:75], v[48:51], off
	s_waitcnt lgkmcnt(0)
	s_nop 0
	v_add_f32_e32 v48, v60, v61
	ds_bpermute_b32 v49, v164, v48
	v_cvt_pk_bf16_f32 v50, v52, v53
	v_cvt_pk_bf16_f32 v51, v54, v55
	v_cvt_pk_bf16_f32 v52, v66, v67
	v_cvt_pk_bf16_f32 v53, v68, v69
	global_store_dwordx4 v[74:75], v[50:53], off offset:256
	s_and_saveexec_b64 s[34:35], s[2:3]
	s_cbranch_execz .LBB0_1153
	v_lshlrev_b64 v[50:51], 6, v[64:65]
	v_lshl_add_u64 v[50:51], s[12:13], 0, v[50:51]
	v_lshl_add_u64 v[50:51], s[30:31], 2, v[50:51]
	s_lshl_b32 s20, s44, 2
	v_lshl_add_u64 v[50:51], v[50:51], 0, s[20:21]
	s_waitcnt lgkmcnt(0)
	v_add_f32_e32 v48, v48, v49
	global_store_dword v[50:51], v48, off
.LBB0_1153:
	s_or_b64 exec, exec, s[34:35]
	v_add_u32_e32 v48, 0x90, v146
	s_waitcnt lgkmcnt(0)
	v_ashrrev_i32_e32 v49, 31, v48
	v_lshlrev_b64 v[50:51], 11, v[48:49]
	v_lshl_add_u64 v[50:51], s[40:41], 0, v[50:51]
	v_lshl_add_u64 v[58:59], v[144:145], 1, v[50:51]
	s_waitcnt vmcnt(10)
	v_lshlrev_b32_e32 v60, 16, v194
	v_and_b32_e32 v61, 0xffff0000, v194
	v_lshlrev_b32_e32 v62, 16, v196
	v_and_b32_e32 v63, 0xffff0000, v196
	v_lshlrev_b32_e32 v50, 16, v195
	v_and_b32_e32 v51, 0xffff0000, v195
	v_lshlrev_b32_e32 v52, 16, v197
	v_and_b32_e32 v53, 0xffff0000, v197
	v_lshlrev_b32_e32 v64, 16, v198
	v_and_b32_e32 v65, 0xffff0000, v198
	v_lshlrev_b32_e32 v66, 16, v200
	v_and_b32_e32 v67, 0xffff0000, v200
	v_lshlrev_b32_e32 v54, 16, v199
	v_and_b32_e32 v55, 0xffff0000, v199
	v_lshlrev_b32_e32 v56, 16, v201
	v_and_b32_e32 v57, 0xffff0000, v201
	v_pk_add_f32 v[44:45], v[44:45], v[60:61]
	v_pk_add_f32 v[40:41], v[40:41], v[62:63]
	v_pk_add_f32 v[46:47], v[46:47], v[50:51]
	v_pk_add_f32 v[42:43], v[42:43], v[52:53]
	v_pk_add_f32 v[36:37], v[36:37], v[64:65]
	v_pk_add_f32 v[50:51], v[32:33], v[66:67]
	v_pk_add_f32 v[38:39], v[38:39], v[54:55]
	v_pk_add_f32 v[52:53], v[34:35], v[56:57]
	v_cvt_pk_bf16_f32 v32, v44, v45
	v_cvt_pk_bf16_f32 v33, v46, v47
	v_pk_mul_f32 v[34:35], v[44:45], v[44:45]
	v_pk_mul_f32 v[44:45], v[46:47], v[46:47]
	v_pk_mul_f32 v[46:47], v[40:41], v[40:41]
	v_pk_mul_f32 v[54:55], v[42:43], v[42:43]
	v_pk_mul_f32 v[56:57], v[36:37], v[36:37]
	v_pk_mul_f32 v[60:61], v[38:39], v[38:39]
	v_pk_mul_f32 v[62:63], v[50:51], v[50:51]
	v_pk_mul_f32 v[64:65], v[52:53], v[52:53]
	v_add_f32_e32 v62, v62, v63
	v_add_f32_e32 v64, v64, v65
	v_add_f32_e32 v60, v60, v61
	v_add_f32_e32 v56, v56, v57
	v_add_f32_e32 v54, v54, v55
	v_add_f32_e32 v46, v46, v47
	v_add_f32_e32 v44, v44, v45
	v_add_f32_e32 v34, v34, v35
	v_add_f32_e32 v35, v62, v64
	v_add_f32_e32 v45, v56, v60
	v_add_f32_e32 v46, v46, v54
	v_add_f32_e32 v34, v34, v44
	v_add_f32_e32 v35, v45, v35
	v_add_f32_e32 v34, v34, v46
	v_add_f32_e32 v44, v34, v35
	ds_bpermute_b32 v45, v165, v44
	v_cvt_pk_bf16_f32 v34, v40, v41
	v_cvt_pk_bf16_f32 v35, v42, v43
	global_store_dwordx4 v[58:59], v[32:35], off
	s_waitcnt lgkmcnt(0)
	s_nop 0
	v_add_f32_e32 v32, v44, v45
	ds_bpermute_b32 v33, v164, v32
	v_cvt_pk_bf16_f32 v34, v36, v37
	v_cvt_pk_bf16_f32 v35, v38, v39
	v_cvt_pk_bf16_f32 v36, v50, v51
	v_cvt_pk_bf16_f32 v37, v52, v53
	global_store_dwordx4 v[58:59], v[34:37], off offset:256
	s_and_saveexec_b64 s[34:35], s[2:3]
	s_cbranch_execz .LBB0_1155
	v_lshlrev_b64 v[34:35], 6, v[48:49]
	v_lshl_add_u64 v[34:35], s[12:13], 0, v[34:35]
	v_lshl_add_u64 v[34:35], s[30:31], 2, v[34:35]
	s_lshl_b32 s20, s44, 2
	v_lshl_add_u64 v[34:35], v[34:35], 0, s[20:21]
	s_waitcnt lgkmcnt(0)
	v_add_f32_e32 v32, v32, v33
	global_store_dword v[34:35], v32, off
.LBB0_1155:
	s_or_b64 exec, exec, s[34:35]
	v_add_u32_e32 v32, 0xa0, v146
	s_waitcnt lgkmcnt(0)
	v_ashrrev_i32_e32 v33, 31, v32
	v_lshlrev_b64 v[34:35], 11, v[32:33]
	v_lshl_add_u64 v[34:35], s[40:41], 0, v[34:35]
	v_lshl_add_u64 v[42:43], v[144:145], 1, v[34:35]
	s_waitcnt vmcnt(8)
	v_lshlrev_b32_e32 v44, 16, v202
	v_and_b32_e32 v45, 0xffff0000, v202
	v_lshlrev_b32_e32 v46, 16, v204
	v_and_b32_e32 v47, 0xffff0000, v204
	v_lshlrev_b32_e32 v34, 16, v203
	v_and_b32_e32 v35, 0xffff0000, v203
	v_lshlrev_b32_e32 v36, 16, v205
	v_and_b32_e32 v37, 0xffff0000, v205
	v_lshlrev_b32_e32 v48, 16, v206
	v_and_b32_e32 v49, 0xffff0000, v206
	v_lshlrev_b32_e32 v50, 16, v208
	v_and_b32_e32 v51, 0xffff0000, v208
	v_lshlrev_b32_e32 v38, 16, v207
	v_and_b32_e32 v39, 0xffff0000, v207
	v_lshlrev_b32_e32 v40, 16, v209
	v_and_b32_e32 v41, 0xffff0000, v209
	v_pk_add_f32 v[28:29], v[28:29], v[44:45]
	v_pk_add_f32 v[24:25], v[24:25], v[46:47]
	v_pk_add_f32 v[30:31], v[30:31], v[34:35]
	v_pk_add_f32 v[26:27], v[26:27], v[36:37]
	v_pk_add_f32 v[20:21], v[20:21], v[48:49]
	v_pk_add_f32 v[34:35], v[16:17], v[50:51]
	v_pk_add_f32 v[22:23], v[22:23], v[38:39]
	v_pk_add_f32 v[36:37], v[18:19], v[40:41]
	v_cvt_pk_bf16_f32 v16, v28, v29
	v_cvt_pk_bf16_f32 v17, v30, v31
	v_pk_mul_f32 v[18:19], v[28:29], v[28:29]
	v_pk_mul_f32 v[28:29], v[30:31], v[30:31]
	v_pk_mul_f32 v[30:31], v[24:25], v[24:25]
	v_pk_mul_f32 v[38:39], v[26:27], v[26:27]
	v_pk_mul_f32 v[40:41], v[20:21], v[20:21]
	v_pk_mul_f32 v[44:45], v[22:23], v[22:23]
	v_pk_mul_f32 v[46:47], v[34:35], v[34:35]
	v_pk_mul_f32 v[48:49], v[36:37], v[36:37]
	v_add_f32_e32 v46, v46, v47
	v_add_f32_e32 v48, v48, v49
	v_add_f32_e32 v44, v44, v45
	v_add_f32_e32 v40, v40, v41
	v_add_f32_e32 v38, v38, v39
	v_add_f32_e32 v30, v30, v31
	v_add_f32_e32 v28, v28, v29
	v_add_f32_e32 v18, v18, v19
	v_add_f32_e32 v19, v46, v48
	v_add_f32_e32 v29, v40, v44
	v_add_f32_e32 v30, v30, v38
	v_add_f32_e32 v18, v18, v28
	v_add_f32_e32 v19, v29, v19
	v_add_f32_e32 v18, v18, v30
	v_add_f32_e32 v28, v18, v19
	ds_bpermute_b32 v29, v165, v28
	v_cvt_pk_bf16_f32 v18, v24, v25
	v_cvt_pk_bf16_f32 v19, v26, v27
	global_store_dwordx4 v[42:43], v[16:19], off
	s_waitcnt lgkmcnt(0)
	s_nop 0
	v_add_f32_e32 v16, v28, v29
	ds_bpermute_b32 v17, v164, v16
	v_cvt_pk_bf16_f32 v18, v20, v21
	v_cvt_pk_bf16_f32 v19, v22, v23
	v_cvt_pk_bf16_f32 v20, v34, v35
	v_cvt_pk_bf16_f32 v21, v36, v37
	global_store_dwordx4 v[42:43], v[18:21], off offset:256
	s_and_saveexec_b64 s[34:35], s[2:3]
	s_cbranch_execz .LBB0_1157
	v_lshlrev_b64 v[18:19], 6, v[32:33]
	v_lshl_add_u64 v[18:19], s[12:13], 0, v[18:19]
	v_lshl_add_u64 v[18:19], s[30:31], 2, v[18:19]
	s_lshl_b32 s20, s44, 2
	v_lshl_add_u64 v[18:19], v[18:19], 0, s[20:21]
	s_waitcnt lgkmcnt(0)
	v_add_f32_e32 v16, v16, v17
	global_store_dword v[18:19], v16, off
.LBB0_1157:
	s_or_b64 exec, exec, s[34:35]
	v_add_u32_e32 v16, 0xb0, v146
	s_waitcnt lgkmcnt(0)
	v_ashrrev_i32_e32 v17, 31, v16
	v_lshlrev_b64 v[18:19], 11, v[16:17]
	v_lshl_add_u64 v[18:19], s[40:41], 0, v[18:19]
	v_lshl_add_u64 v[26:27], v[144:145], 1, v[18:19]
	s_waitcnt vmcnt(6)
	v_lshlrev_b32_e32 v28, 16, v212
	v_and_b32_e32 v29, 0xffff0000, v212
	v_lshlrev_b32_e32 v30, 16, v214
	v_and_b32_e32 v31, 0xffff0000, v214
	v_lshlrev_b32_e32 v18, 16, v213
	v_and_b32_e32 v19, 0xffff0000, v213
	v_lshlrev_b32_e32 v20, 16, v215
	v_and_b32_e32 v21, 0xffff0000, v215
	v_lshlrev_b32_e32 v32, 16, v216
	v_and_b32_e32 v33, 0xffff0000, v216
	v_lshlrev_b32_e32 v34, 16, v218
	v_and_b32_e32 v35, 0xffff0000, v218
	v_lshlrev_b32_e32 v22, 16, v217
	v_and_b32_e32 v23, 0xffff0000, v217
	v_lshlrev_b32_e32 v24, 16, v219
	v_and_b32_e32 v25, 0xffff0000, v219
	v_pk_add_f32 v[12:13], v[12:13], v[28:29]
	v_pk_add_f32 v[8:9], v[8:9], v[30:31]
	v_pk_add_f32 v[14:15], v[14:15], v[18:19]
	v_pk_add_f32 v[10:11], v[10:11], v[20:21]
	v_pk_add_f32 v[4:5], v[4:5], v[32:33]
	v_pk_add_f32 v[18:19], v[0:1], v[34:35]
	v_pk_add_f32 v[6:7], v[6:7], v[22:23]
	v_pk_add_f32 v[20:21], v[2:3], v[24:25]
	v_cvt_pk_bf16_f32 v0, v12, v13
	v_cvt_pk_bf16_f32 v1, v14, v15
	v_pk_mul_f32 v[2:3], v[12:13], v[12:13]
	v_pk_mul_f32 v[12:13], v[14:15], v[14:15]
	v_pk_mul_f32 v[14:15], v[8:9], v[8:9]
	v_pk_mul_f32 v[22:23], v[10:11], v[10:11]
	v_pk_mul_f32 v[24:25], v[4:5], v[4:5]
	v_pk_mul_f32 v[28:29], v[6:7], v[6:7]
	v_pk_mul_f32 v[30:31], v[18:19], v[18:19]
	v_pk_mul_f32 v[32:33], v[20:21], v[20:21]
	v_add_f32_e32 v30, v30, v31
	v_add_f32_e32 v32, v32, v33
	v_add_f32_e32 v28, v28, v29
	v_add_f32_e32 v24, v24, v25
	v_add_f32_e32 v22, v22, v23
	v_add_f32_e32 v14, v14, v15
	v_add_f32_e32 v12, v12, v13
	v_add_f32_e32 v2, v2, v3
	v_add_f32_e32 v3, v30, v32
	v_add_f32_e32 v13, v24, v28
	v_add_f32_e32 v14, v14, v22
	v_add_f32_e32 v2, v2, v12
	v_add_f32_e32 v3, v13, v3
	v_add_f32_e32 v2, v2, v14
	v_add_f32_e32 v12, v2, v3
	ds_bpermute_b32 v13, v165, v12
	v_cvt_pk_bf16_f32 v2, v8, v9
	v_cvt_pk_bf16_f32 v3, v10, v11
	global_store_dwordx4 v[26:27], v[0:3], off
	s_waitcnt lgkmcnt(0)
	s_nop 0
	v_add_f32_e32 v0, v12, v13
	ds_bpermute_b32 v1, v164, v0
	v_cvt_pk_bf16_f32 v2, v4, v5
	v_cvt_pk_bf16_f32 v3, v6, v7
	v_cvt_pk_bf16_f32 v4, v18, v19
	v_cvt_pk_bf16_f32 v5, v20, v21
	global_store_dwordx4 v[26:27], v[2:5], off offset:256
	s_and_saveexec_b64 s[34:35], s[2:3]
	s_cbranch_execz .LBB0_1159
	v_lshlrev_b64 v[2:3], 6, v[16:17]
	v_lshl_add_u64 v[2:3], s[12:13], 0, v[2:3]
	v_lshl_add_u64 v[2:3], s[30:31], 2, v[2:3]
	s_lshl_b32 s20, s44, 2
	v_lshl_add_u64 v[2:3], v[2:3], 0, s[20:21]
	s_waitcnt lgkmcnt(0)
	v_add_f32_e32 v0, v0, v1
	global_store_dword v[2:3], v0, off

	.amdhsa_kernel _Z6mk_fwd4Args
		.amdhsa_group_segment_fixed_size 0
		.amdhsa_private_segment_fixed_size 0
		.amdhsa_kernarg_size 512
		.amdhsa_user_sgpr_count 2
		.amdhsa_user_sgpr_dispatch_ptr 0
		.amdhsa_user_sgpr_queue_ptr 0
		.amdhsa_user_sgpr_kernarg_segment_ptr 1
		.amdhsa_user_sgpr_dispatch_id 0
		.amdhsa_user_sgpr_kernarg_preload_length 0
		.amdhsa_user_sgpr_kernarg_preload_offset 0
		.amdhsa_user_sgpr_private_segment_size 0
		.amdhsa_uses_dynamic_stack 0
		.amdhsa_enable_private_segment 0
		.amdhsa_system_sgpr_workgroup_id_x 1
		.amdhsa_system_sgpr_workgroup_id_y 0
		.amdhsa_system_sgpr_workgroup_id_z 0
		.amdhsa_system_sgpr_workgroup_info 0
		.amdhsa_system_vgpr_workitem_id 2
		.amdhsa_next_free_vgpr 255
		.amdhsa_next_free_sgpr 102
		.amdhsa_accum_offset 256
		.amdhsa_reserve_vcc 1
		.amdhsa_float_round_mode_32 0
		.amdhsa_float_round_mode_16_64 0
		.amdhsa_float_denorm_mode_32 3
		.amdhsa_float_denorm_mode_16_64 3
		.amdhsa_dx10_clamp 1
		.amdhsa_ieee_mode 1
		.amdhsa_fp16_overflow 0
		.amdhsa_tg_split 0
		.amdhsa_exception_fp_ieee_invalid_op 0
		.amdhsa_exception_fp_denorm_src 0
		.amdhsa_exception_fp_ieee_div_zero 0
		.amdhsa_exception_fp_ieee_overflow 0
		.amdhsa_exception_fp_ieee_underflow 0
		.amdhsa_exception_fp_ieee_inexact 0
		.amdhsa_exception_int_div_zero 0
	.end_amdhsa_kernel

amdhsa.kernels:
  - .agpr_count:     0
    .args:
      - .offset:         0
        .size:           256
        .value_kind:     by_value
      - .offset:         256
        .size:           4
        .value_kind:     hidden_block_count_x
      - .offset:         260
        .size:           4
        .value_kind:     hidden_block_count_y
      - .offset:         264
        .size:           4
        .value_kind:     hidden_block_count_z
      - .offset:         268
        .size:           2
        .value_kind:     hidden_group_size_x
      - .offset:         270
        .size:           2
        .value_kind:     hidden_group_size_y
      - .offset:         272
        .size:           2
        .value_kind:     hidden_group_size_z
      - .offset:         274
        .size:           2
        .value_kind:     hidden_remainder_x
      - .offset:         276
        .size:           2
        .value_kind:     hidden_remainder_y
      - .offset:         278
        .size:           2
        .value_kind:     hidden_remainder_z
      - .offset:         296
        .size:           8
        .value_kind:     hidden_global_offset_x
      - .offset:         304
        .size:           8
        .value_kind:     hidden_global_offset_y
      - .offset:         312
        .size:           8
        .value_kind:     hidden_global_offset_z
      - .offset:         320
        .size:           2
        .value_kind:     hidden_grid_dims
      - .offset:         344
        .size:           8
        .value_kind:     hidden_multigrid_sync_arg
      - .offset:         376
        .size:           4
        .value_kind:     hidden_dynamic_lds_size
    .group_segment_fixed_size: 0
    .kernarg_segment_align: 8
    .kernarg_segment_size: 512
    .language:       OpenCL C
    .language_version:
      - 2
      - 0
    .max_flat_workgroup_size: 512
    .name:           _Z6mk_fwd4Args
    .private_segment_fixed_size: 0
    .sgpr_count:     108
    .sgpr_spill_count: 43
    .symbol:         _Z6mk_fwd4Args.kd
    .uniform_work_group_size: 1
    .uses_dynamic_stack: false
    .vgpr_count:     255
    .vgpr_spill_count: 0
    .wavefront_size: 64
